# same as previous but each removed wave-private barrier replaced by s_nop 0 to preserve compiler wait-state distances
# baseline (speedup 1.0000x reference)
; __device__ __forceinline__ void s5_bu16(const S5Frag& f, const bf16x8 uf, float* buL, int lane) {
;     const int jj = lane & 15, quad = lane >> 4;
; #pragma unroll
;     for (int nt = 0; nt < 4; ++nt) {
;         const f32x4 z = (f32x4){0.f, 0.f, 0.f, 0.f};
;         const f32x4 dre = __builtin_amdgcn_mfma_f32_16x16x32_bf16(uf, f.bfr[nt], z, 0, 0, 0);
;         const f32x4 dim = __builtin_amdgcn_mfma_f32_16x16x32_bf16(uf, f.bfr[nt + 4], z, 0, 0, 0);
; #pragma unroll
;         for (int r = 0; r < 4; ++r) *(f32x2*)(buL + ((4 * quad + r) * 64 + 16 * nt + jj) * 2) = (f32x2){dre[r], dim[r]};
;     }
; }
; __device__ __forceinline__ void s5_pass1_item(PP p, unsigned char* shm, int item, int l) {
;     ...
;     s5_write_bbl(q, bbL, lane);
;     __syncthreads();
;     S5Frag f; s5_load_frags(bbL, f, lane);
;     f32x2 x = (f32x2){0.f, 0.f};
; #pragma unroll
;     for (int sc = 0; sc < 4; ++sc) {
;         s5_bu16(f, uf[sc], buL, lane);
;         __syncthreads();
; #pragma unroll
;         for (int t = 0; t < 16; ++t) s5_rec(q, *(const f32x2*)(buL + (t * 64 + lane) * 2), x);
.LBB0_552:
	s_or_b64 exec, exec, s[2:3]
	v_mul_f32_e32 v50, v59, v57
	v_lshl_add_u32 v52, v56, 13, 0
	s_waitcnt lgkmcnt(1)
	v_mfma_f32_16x16x32_bf16 v[56:59], v[46:49], v[26:29], 0
	v_and_b32_e32 v0, 0x600, v51
	v_lshl_add_u32 v51, v0, 2, v52
	v_lshlrev_b32_e32 v0, 3, v55
	v_mfma_f32_16x16x32_bf16 v[60:63], v[46:49], v[38:41], 0
	v_and_b32_e32 v55, 0x78, v0
	s_nop 2
	v_mov_b32_e32 v68, v56
	v_mov_b32_e32 v70, v58
	s_waitcnt lgkmcnt(0)
	v_mfma_f32_16x16x32_bf16 v[64:67], v[46:49], v[34:37], 0
	v_add_u32_e32 v74, v51, v55
	v_mov_b32_e32 v69, v60
	v_mov_b32_e32 v60, v57
	v_mov_b32_e32 v71, v62
	v_mov_b32_e32 v62, v59
	v_mfma_f32_16x16x32_bf16 v[56:59], v[46:49], v[14:17], 0
	v_or_b32_e32 v55, 0x180, v0
	v_add_u32_e32 v55, v51, v55
	v_add_u32_e32 v51, v52, v0
	v_mov_b32_e32 v52, v53
	v_mov_b32_e32 v73, v64
	s_nop 2
	v_mov_b32_e32 v72, v56
	v_add_u32_e32 v53, 0x1000, v74
	v_mov_b32_e32 v64, v57
	v_mov_b32_e32 v56, v58
	v_mov_b32_e32 v57, v66
	ds_write2_b64 v53, v[68:69], v[72:73] offset1:16
	ds_write2_b64 v53, v[70:71], v[56:57] offset0:128 offset1:144
	v_mov_b32_e32 v66, v59
	v_mfma_f32_16x16x32_bf16 v[56:59], v[46:49], v[6:9], 0
	v_readlane_b32 s2, v255, 9
	v_readlane_b32 s3, v255, 10
	s_mov_b32 s3, s19
	v_mfma_f32_16x16x32_bf16 v[68:71], v[46:49], v[18:21], 0
	s_mov_b32 s18, s2
	s_nop 2
	v_mov_b32_e32 v72, v56
	v_mov_b32_e32 v56, v58
	v_writelane_b32 v255, s18, 9
	s_nop 1
	v_writelane_b32 v255, s19, 10
	v_mov_b32_e32 v73, v68
	v_mov_b32_e32 v68, v57
	v_mov_b32_e32 v57, v70
	ds_write2_b64 v53, v[56:57], v[62:63] offset0:160 offset1:192
	v_mov_b32_e32 v70, v59
	v_mfma_f32_16x16x32_bf16 v[56:59], v[46:49], v[10:13], 0
	ds_write2_b64 v53, v[72:73], v[60:61] offset0:32 offset1:64
	ds_write2_b64 v53, v[64:65], v[68:69] offset0:80 offset1:96
	ds_write2_b64 v53, v[66:67], v[70:71] offset0:208 offset1:224
	v_mfma_f32_16x16x32_bf16 v[46:49], v[46:49], v[22:25], 0
	s_nop 3
	v_mov_b32_e32 v60, v56
	s_nop 2
	v_mov_b32_e32 v61, v46
	v_mov_b32_e32 v46, v57
	ds_write2st64_b64 v55, v[60:61], v[46:47] offset0:8 offset1:9
	v_mov_b32_e32 v46, v58
	v_mov_b32_e32 v47, v48
	v_mov_b32_e32 v48, v59
	ds_write2st64_b64 v55, v[46:47], v[48:49] offset0:10 offset1:11
	s_waitcnt lgkmcnt(0)
	s_nop 0
	ds_read2st64_b64 v[180:183], v51 offset0:8 offset1:9
	ds_read2st64_b64 v[184:187], v51 offset0:10 offset1:11
	ds_read2st64_b64 v[188:191], v51 offset0:12 offset1:13
	ds_read2st64_b64 v[192:195], v51 offset0:14 offset1:15
	ds_read2st64_b64 v[196:199], v51 offset0:16 offset1:17
	ds_read2st64_b64 v[200:203], v51 offset0:18 offset1:19
	ds_read2st64_b64 v[204:207], v51 offset0:20 offset1:21
	ds_read2st64_b64 v[208:211], v51 offset0:22 offset1:23
	v_pk_mul_f32 v[56:57], v[52:53], s[2:3] op_sel_hi:[0,1]
	v_pk_fma_f32 v[56:57], v[50:51], 0, v[56:57] op_sel_hi:[0,0,1]
	v_mfma_f32_16x16x32_bf16 v[60:63], v[42:45], v[34:37], 0
	s_lshl_b32 s2, s34, 10
	s_waitcnt lgkmcnt(7)
	v_pk_add_f32 v[46:47], v[56:57], v[180:181]
	s_lshl_b32 s3, s9, 5
	v_xor_b32_e32 v56, 0x80000000, v47
	v_mov_b32_e32 v57, v46
	v_pk_mul_f32 v[56:57], v[52:53], v[56:57] op_sel_hi:[0,1]
	v_pk_fma_f32 v[46:47], v[50:51], v[46:47], v[56:57] op_sel_hi:[0,1,1]
	v_pk_add_f32 v[56:57], v[182:183], v[46:47]
	v_xor_b32_e32 v58, 0x80000000, v57
	v_mov_b32_e32 v59, v56
	v_pk_mul_f32 v[58:59], v[52:53], v[58:59] op_sel_hi:[0,1]
	v_pk_fma_f32 v[56:57], v[50:51], v[56:57], v[58:59] op_sel_hi:[0,1,1]
	s_waitcnt lgkmcnt(6)
	v_pk_add_f32 v[46:47], v[184:185], v[56:57]
	v_mov_b32_e32 v71, v60
	v_xor_b32_e32 v56, 0x80000000, v47
	v_mov_b32_e32 v57, v46
	v_pk_mul_f32 v[56:57], v[52:53], v[56:57] op_sel_hi:[0,1]
	v_pk_fma_f32 v[46:47], v[50:51], v[46:47], v[56:57] op_sel_hi:[0,1,1]
	v_pk_add_f32 v[56:57], v[186:187], v[46:47]
	v_xor_b32_e32 v58, 0x80000000, v57
	v_mov_b32_e32 v59, v56
	v_pk_mul_f32 v[58:59], v[52:53], v[58:59] op_sel_hi:[0,1]
	v_pk_fma_f32 v[56:57], v[50:51], v[56:57], v[58:59] op_sel_hi:[0,1,1]
	s_waitcnt lgkmcnt(5)
	v_pk_add_f32 v[46:47], v[188:189], v[56:57]
	s_add_i32 s3, s3, s2
	v_xor_b32_e32 v56, 0x80000000, v47
	v_mov_b32_e32 v57, v46
	v_pk_mul_f32 v[56:57], v[52:53], v[56:57] op_sel_hi:[0,1]
	v_pk_fma_f32 v[46:47], v[50:51], v[46:47], v[56:57] op_sel_hi:[0,1,1]
	v_pk_add_f32 v[56:57], v[190:191], v[46:47]
	v_xor_b32_e32 v58, 0x80000000, v57
	v_mov_b32_e32 v59, v56
	v_pk_mul_f32 v[58:59], v[52:53], v[58:59] op_sel_hi:[0,1]
	v_pk_fma_f32 v[56:57], v[50:51], v[56:57], v[58:59] op_sel_hi:[0,1,1]
	s_waitcnt lgkmcnt(4)
	v_pk_add_f32 v[46:47], v[192:193], v[56:57]
	s_nop 0
	v_xor_b32_e32 v56, 0x80000000, v47
	v_mov_b32_e32 v57, v46
	v_pk_mul_f32 v[56:57], v[52:53], v[56:57] op_sel_hi:[0,1]
	v_pk_fma_f32 v[46:47], v[50:51], v[46:47], v[56:57] op_sel_hi:[0,1,1]
	v_pk_add_f32 v[56:57], v[194:195], v[46:47]
	v_xor_b32_e32 v58, 0x80000000, v57
	v_mov_b32_e32 v59, v56
	v_pk_mul_f32 v[58:59], v[52:53], v[58:59] op_sel_hi:[0,1]
	v_pk_fma_f32 v[56:57], v[50:51], v[56:57], v[58:59] op_sel_hi:[0,1,1]
	s_waitcnt lgkmcnt(3)
	v_pk_add_f32 v[46:47], v[196:197], v[56:57]
	s_nop 0
	v_xor_b32_e32 v56, 0x80000000, v47
	v_mov_b32_e32 v57, v46
	v_pk_mul_f32 v[56:57], v[52:53], v[56:57] op_sel_hi:[0,1]
	v_pk_fma_f32 v[46:47], v[50:51], v[46:47], v[56:57] op_sel_hi:[0,1,1]
	v_pk_add_f32 v[56:57], v[198:199], v[46:47]
	v_xor_b32_e32 v58, 0x80000000, v57
	v_mov_b32_e32 v59, v56
	v_pk_mul_f32 v[58:59], v[52:53], v[58:59] op_sel_hi:[0,1]
	v_pk_fma_f32 v[56:57], v[50:51], v[56:57], v[58:59] op_sel_hi:[0,1,1]
	s_waitcnt lgkmcnt(2)
; __device__ __forceinline__ void s5_bu16(const S5Frag& f, const bf16x8 uf, float* buL, int lane) {
;     const int jj = lane & 15, quad = lane >> 4;
; #pragma unroll
;     for (int nt = 0; nt < 4; ++nt) {
;         const f32x4 z = (f32x4){0.f, 0.f, 0.f, 0.f};
;         const f32x4 dre = __builtin_amdgcn_mfma_f32_16x16x32_bf16(uf, f.bfr[nt], z, 0, 0, 0);
;         const f32x4 dim = __builtin_amdgcn_mfma_f32_16x16x32_bf16(uf, f.bfr[nt + 4], z, 0, 0, 0);
; #pragma unroll
;         for (int r = 0; r < 4; ++r) *(f32x2*)(buL + ((4 * quad + r) * 64 + 16 * nt + jj) * 2) = (f32x2){dre[r], dim[r]};
;     }
; }
; __device__ __forceinline__ void s5_pass1_item(PP p, unsigned char* shm, int item, int l) {
;     ...
; #pragma unroll
;     for (int sc = 0; sc < 4; ++sc) {
;         s5_bu16(f, uf[sc], buL, lane);
;         __syncthreads();
; #pragma unroll
;         for (int t = 0; t < 16; ++t) s5_rec(q, *(const f32x2*)(buL + (t * 64 + lane) * 2), x);
;         __syncthreads();
	v_pk_add_f32 v[46:47], v[200:201], v[56:57]
	s_nop 0
	v_xor_b32_e32 v56, 0x80000000, v47
	v_mov_b32_e32 v57, v46
	v_pk_mul_f32 v[56:57], v[52:53], v[56:57] op_sel_hi:[0,1]
	v_pk_fma_f32 v[46:47], v[50:51], v[46:47], v[56:57] op_sel_hi:[0,1,1]
	v_pk_add_f32 v[56:57], v[202:203], v[46:47]
	v_xor_b32_e32 v58, 0x80000000, v57
	v_mov_b32_e32 v59, v56
	v_pk_mul_f32 v[58:59], v[52:53], v[58:59] op_sel_hi:[0,1]
	v_pk_fma_f32 v[56:57], v[50:51], v[56:57], v[58:59] op_sel_hi:[0,1,1]
	s_waitcnt lgkmcnt(1)
	v_pk_add_f32 v[46:47], v[204:205], v[56:57]
	s_nop 0
	v_xor_b32_e32 v56, 0x80000000, v47
	v_mov_b32_e32 v57, v46
	v_pk_mul_f32 v[56:57], v[52:53], v[56:57] op_sel_hi:[0,1]
	v_pk_fma_f32 v[46:47], v[50:51], v[46:47], v[56:57] op_sel_hi:[0,1,1]
	v_pk_add_f32 v[56:57], v[206:207], v[46:47]
	v_xor_b32_e32 v58, 0x80000000, v57
	v_mov_b32_e32 v59, v56
	v_pk_mul_f32 v[58:59], v[52:53], v[58:59] op_sel_hi:[0,1]
	v_pk_fma_f32 v[56:57], v[50:51], v[56:57], v[58:59] op_sel_hi:[0,1,1]
	s_waitcnt lgkmcnt(0)
	v_pk_add_f32 v[46:47], v[208:209], v[56:57]
	s_nop 0
	v_xor_b32_e32 v56, 0x80000000, v47
	v_mov_b32_e32 v57, v46
	v_pk_mul_f32 v[56:57], v[52:53], v[56:57] op_sel_hi:[0,1]
	v_pk_fma_f32 v[46:47], v[50:51], v[46:47], v[56:57] op_sel_hi:[0,1,1]
	v_pk_add_f32 v[68:69], v[210:211], v[46:47]
	v_mfma_f32_16x16x32_bf16 v[46:49], v[42:45], v[26:29], 0
	s_nop 0
	v_mfma_f32_16x16x32_bf16 v[56:59], v[42:45], v[38:41], 0
	s_nop 5
	v_mov_b32_e32 v64, v46
	s_nop 0
	v_mov_b32_e32 v65, v56
	v_mov_b32_e32 v56, v47
	v_mov_b32_e32 v66, v48
	v_mov_b32_e32 v67, v58
	v_mov_b32_e32 v58, v49
	v_mfma_f32_16x16x32_bf16 v[46:49], v[42:45], v[14:17], 0
	s_nop 7
	v_mov_b32_e32 v70, v46
	v_mov_b32_e32 v60, v47
	v_mov_b32_e32 v46, v48
	v_mov_b32_e32 v47, v62
	ds_write2_b64 v53, v[64:65], v[70:71] offset1:16
	ds_write2_b64 v53, v[66:67], v[46:47] offset0:128 offset1:144
	v_mov_b32_e32 v62, v49
	v_mfma_f32_16x16x32_bf16 v[46:49], v[42:45], v[6:9], 0
	v_mfma_f32_16x16x32_bf16 v[64:67], v[42:45], v[18:21], 0
	s_nop 6
	v_mov_b32_e32 v70, v46
	v_mov_b32_e32 v71, v64
	v_mov_b32_e32 v64, v47
	v_mov_b32_e32 v46, v48
	v_mov_b32_e32 v47, v66
	ds_write2_b64 v53, v[46:47], v[58:59] offset0:160 offset1:192
	v_mov_b32_e32 v66, v49
	v_mfma_f32_16x16x32_bf16 v[46:49], v[42:45], v[10:13], 0
	ds_write2_b64 v53, v[70:71], v[56:57] offset0:32 offset1:64
	ds_write2_b64 v53, v[60:61], v[64:65] offset0:80 offset1:96
	ds_write2_b64 v53, v[62:63], v[66:67] offset0:208 offset1:224
	v_mfma_f32_16x16x32_bf16 v[42:45], v[42:45], v[22:25], 0
	s_nop 3
	v_mov_b32_e32 v56, v46
	s_nop 2
	v_mov_b32_e32 v57, v42
	v_mov_b32_e32 v42, v47
	ds_write2st64_b64 v55, v[56:57], v[42:43] offset0:8 offset1:9
	v_mov_b32_e32 v42, v48
	v_mov_b32_e32 v43, v44
	v_mov_b32_e32 v44, v49
	ds_write2st64_b64 v55, v[42:43], v[44:45] offset0:10 offset1:11
	s_waitcnt lgkmcnt(0)
	s_nop 0
	ds_read2st64_b64 v[180:183], v51 offset0:8 offset1:9
	ds_read2st64_b64 v[184:187], v51 offset0:10 offset1:11
	ds_read2st64_b64 v[188:191], v51 offset0:12 offset1:13
	ds_read2st64_b64 v[192:195], v51 offset0:14 offset1:15
	ds_read2st64_b64 v[196:199], v51 offset0:16 offset1:17
	ds_read2st64_b64 v[200:203], v51 offset0:18 offset1:19
	ds_read2st64_b64 v[204:207], v51 offset0:20 offset1:21
	ds_read2st64_b64 v[208:211], v51 offset0:22 offset1:23
	v_xor_b32_e32 v46, 0x80000000, v69
	v_mov_b32_e32 v47, v68
	v_pk_mul_f32 v[46:47], v[52:53], v[46:47] op_sel_hi:[0,1]
	v_pk_fma_f32 v[46:47], v[50:51], v[68:69], v[46:47] op_sel_hi:[0,1,1]
	s_waitcnt lgkmcnt(7)
	v_pk_add_f32 v[42:43], v[180:181], v[46:47]
	v_mfma_f32_16x16x32_bf16 v[56:59], v[30:33], v[34:37], 0
	v_xor_b32_e32 v46, 0x80000000, v43
	v_mov_b32_e32 v47, v42
	v_pk_mul_f32 v[46:47], v[52:53], v[46:47] op_sel_hi:[0,1]
	v_pk_fma_f32 v[42:43], v[50:51], v[42:43], v[46:47] op_sel_hi:[0,1,1]
	v_pk_add_f32 v[46:47], v[182:183], v[42:43]
	v_xor_b32_e32 v48, 0x80000000, v47
	v_mov_b32_e32 v49, v46
	v_pk_mul_f32 v[48:49], v[52:53], v[48:49] op_sel_hi:[0,1]
	v_pk_fma_f32 v[46:47], v[50:51], v[46:47], v[48:49] op_sel_hi:[0,1,1]
	s_waitcnt lgkmcnt(6)
	v_pk_add_f32 v[42:43], v[184:185], v[46:47]
	v_mov_b32_e32 v67, v56
	v_xor_b32_e32 v46, 0x80000000, v43
	v_mov_b32_e32 v47, v42
	v_pk_mul_f32 v[46:47], v[52:53], v[46:47] op_sel_hi:[0,1]
	v_pk_fma_f32 v[42:43], v[50:51], v[42:43], v[46:47] op_sel_hi:[0,1,1]
	v_pk_add_f32 v[46:47], v[186:187], v[42:43]
	v_xor_b32_e32 v48, 0x80000000, v47
	v_mov_b32_e32 v49, v46
	v_pk_mul_f32 v[48:49], v[52:53], v[48:49] op_sel_hi:[0,1]
	v_pk_fma_f32 v[46:47], v[50:51], v[46:47], v[48:49] op_sel_hi:[0,1,1]
	s_waitcnt lgkmcnt(5)
	v_pk_add_f32 v[42:43], v[188:189], v[46:47]
	s_nop 0
	v_xor_b32_e32 v46, 0x80000000, v43
	v_mov_b32_e32 v47, v42
	v_pk_mul_f32 v[46:47], v[52:53], v[46:47] op_sel_hi:[0,1]
	v_pk_fma_f32 v[42:43], v[50:51], v[42:43], v[46:47] op_sel_hi:[0,1,1]
	v_pk_add_f32 v[46:47], v[190:191], v[42:43]
	v_xor_b32_e32 v48, 0x80000000, v47
	v_mov_b32_e32 v49, v46
	v_pk_mul_f32 v[48:49], v[52:53], v[48:49] op_sel_hi:[0,1]
	v_pk_fma_f32 v[46:47], v[50:51], v[46:47], v[48:49] op_sel_hi:[0,1,1]
	s_waitcnt lgkmcnt(4)
	v_pk_add_f32 v[42:43], v[192:193], v[46:47]
	s_nop 0
	v_xor_b32_e32 v46, 0x80000000, v43
	v_mov_b32_e32 v47, v42
	v_pk_mul_f32 v[46:47], v[52:53], v[46:47] op_sel_hi:[0,1]
	v_pk_fma_f32 v[42:43], v[50:51], v[42:43], v[46:47] op_sel_hi:[0,1,1]
	v_pk_add_f32 v[46:47], v[194:195], v[42:43]
	v_xor_b32_e32 v48, 0x80000000, v47
	v_mov_b32_e32 v49, v46
	v_pk_mul_f32 v[48:49], v[52:53], v[48:49] op_sel_hi:[0,1]
	v_pk_fma_f32 v[46:47], v[50:51], v[46:47], v[48:49] op_sel_hi:[0,1,1]
	s_waitcnt lgkmcnt(3)
; __device__ __forceinline__ void s5_bu16(const S5Frag& f, const bf16x8 uf, float* buL, int lane) {
;     const int jj = lane & 15, quad = lane >> 4;
; #pragma unroll
;     for (int nt = 0; nt < 4; ++nt) {
;         const f32x4 z = (f32x4){0.f, 0.f, 0.f, 0.f};
;         const f32x4 dre = __builtin_amdgcn_mfma_f32_16x16x32_bf16(uf, f.bfr[nt], z, 0, 0, 0);
;         const f32x4 dim = __builtin_amdgcn_mfma_f32_16x16x32_bf16(uf, f.bfr[nt + 4], z, 0, 0, 0);
; #pragma unroll
;         for (int r = 0; r < 4; ++r) *(f32x2*)(buL + ((4 * quad + r) * 64 + 16 * nt + jj) * 2) = (f32x2){dre[r], dim[r]};
;     }
; }
; __device__ __forceinline__ void s5_pass1_item(PP p, unsigned char* shm, int item, int l) {
;     ...
; #pragma unroll
;     for (int sc = 0; sc < 4; ++sc) {
;         s5_bu16(f, uf[sc], buL, lane);
;         __syncthreads();
; #pragma unroll
;         for (int t = 0; t < 16; ++t) s5_rec(q, *(const f32x2*)(buL + (t * 64 + lane) * 2), x);
;         __syncthreads();
	v_pk_add_f32 v[42:43], v[196:197], v[46:47]
	s_nop 0
	v_xor_b32_e32 v46, 0x80000000, v43
	v_mov_b32_e32 v47, v42
	v_pk_mul_f32 v[46:47], v[52:53], v[46:47] op_sel_hi:[0,1]
	v_pk_fma_f32 v[42:43], v[50:51], v[42:43], v[46:47] op_sel_hi:[0,1,1]
	v_pk_add_f32 v[46:47], v[198:199], v[42:43]
	v_xor_b32_e32 v48, 0x80000000, v47
	v_mov_b32_e32 v49, v46
	v_pk_mul_f32 v[48:49], v[52:53], v[48:49] op_sel_hi:[0,1]
	v_pk_fma_f32 v[46:47], v[50:51], v[46:47], v[48:49] op_sel_hi:[0,1,1]
	s_waitcnt lgkmcnt(2)
	v_pk_add_f32 v[42:43], v[200:201], v[46:47]
	s_nop 0
	v_xor_b32_e32 v46, 0x80000000, v43
	v_mov_b32_e32 v47, v42
	v_pk_mul_f32 v[46:47], v[52:53], v[46:47] op_sel_hi:[0,1]
	v_pk_fma_f32 v[42:43], v[50:51], v[42:43], v[46:47] op_sel_hi:[0,1,1]
	v_pk_add_f32 v[46:47], v[202:203], v[42:43]
	v_xor_b32_e32 v48, 0x80000000, v47
	v_mov_b32_e32 v49, v46
	v_pk_mul_f32 v[48:49], v[52:53], v[48:49] op_sel_hi:[0,1]
	v_pk_fma_f32 v[46:47], v[50:51], v[46:47], v[48:49] op_sel_hi:[0,1,1]
	s_waitcnt lgkmcnt(1)
	v_pk_add_f32 v[42:43], v[204:205], v[46:47]
	s_nop 0
	v_xor_b32_e32 v46, 0x80000000, v43
	v_mov_b32_e32 v47, v42
	v_pk_mul_f32 v[46:47], v[52:53], v[46:47] op_sel_hi:[0,1]
	v_pk_fma_f32 v[42:43], v[50:51], v[42:43], v[46:47] op_sel_hi:[0,1,1]
	v_pk_add_f32 v[46:47], v[206:207], v[42:43]
	v_xor_b32_e32 v48, 0x80000000, v47
	v_mov_b32_e32 v49, v46
	v_pk_mul_f32 v[48:49], v[52:53], v[48:49] op_sel_hi:[0,1]
	v_pk_fma_f32 v[46:47], v[50:51], v[46:47], v[48:49] op_sel_hi:[0,1,1]
	s_waitcnt lgkmcnt(0)
	v_pk_add_f32 v[42:43], v[208:209], v[46:47]
	s_nop 0
	v_xor_b32_e32 v46, 0x80000000, v43
	v_mov_b32_e32 v47, v42
	v_pk_mul_f32 v[46:47], v[52:53], v[46:47] op_sel_hi:[0,1]
	v_pk_fma_f32 v[42:43], v[50:51], v[42:43], v[46:47] op_sel_hi:[0,1,1]
	v_pk_add_f32 v[64:65], v[210:211], v[42:43]
	v_mfma_f32_16x16x32_bf16 v[42:45], v[30:33], v[26:29], 0
	s_nop 0
	v_mfma_f32_16x16x32_bf16 v[46:49], v[30:33], v[38:41], 0
	v_mfma_f32_16x16x32_bf16 v[26:29], v[2:5], v[26:29], 0
	s_nop 4
	v_mov_b32_e32 v60, v42
	s_nop 0
	v_mov_b32_e32 v61, v46
	v_mov_b32_e32 v46, v43
	v_mov_b32_e32 v62, v44
	v_mov_b32_e32 v63, v48
	v_mov_b32_e32 v48, v45
	v_mfma_f32_16x16x32_bf16 v[42:45], v[30:33], v[14:17], 0
	v_mfma_f32_16x16x32_bf16 v[14:17], v[2:5], v[14:17], 0
	s_nop 6
	v_mov_b32_e32 v66, v42
	v_mov_b32_e32 v56, v43
	v_mov_b32_e32 v42, v44
	v_mov_b32_e32 v43, v58
	ds_write2_b64 v53, v[60:61], v[66:67] offset1:16
	ds_write2_b64 v53, v[62:63], v[42:43] offset0:128 offset1:144
	v_mov_b32_e32 v58, v45
	v_mfma_f32_16x16x32_bf16 v[42:45], v[30:33], v[6:9], 0
	v_mfma_f32_16x16x32_bf16 v[60:63], v[30:33], v[18:21], 0
	v_mfma_f32_16x16x32_bf16 v[6:9], v[2:5], v[6:9], 0
	s_nop 5
	v_mov_b32_e32 v66, v42
	v_mov_b32_e32 v67, v60
	v_mov_b32_e32 v60, v43
	v_mov_b32_e32 v42, v44
	v_mov_b32_e32 v43, v62
	ds_write2_b64 v53, v[42:43], v[48:49] offset0:160 offset1:192
	v_mov_b32_e32 v62, v45
	v_mfma_f32_16x16x32_bf16 v[42:45], v[30:33], v[10:13], 0
	ds_write2_b64 v53, v[66:67], v[46:47] offset0:32 offset1:64
	ds_write2_b64 v53, v[56:57], v[60:61] offset0:80 offset1:96
	ds_write2_b64 v53, v[58:59], v[62:63] offset0:208 offset1:224
	v_mfma_f32_16x16x32_bf16 v[30:33], v[30:33], v[22:25], 0
	s_nop 3
	v_mov_b32_e32 v46, v42
	s_nop 2
	v_mov_b32_e32 v47, v30
	v_mov_b32_e32 v30, v43
	ds_write2st64_b64 v55, v[46:47], v[30:31] offset0:8 offset1:9
	v_mov_b32_e32 v30, v44
	v_mov_b32_e32 v31, v32
	v_mov_b32_e32 v32, v45
	ds_write2st64_b64 v55, v[30:31], v[32:33] offset0:10 offset1:11
	s_waitcnt lgkmcnt(0)
	s_nop 0
	ds_read2st64_b64 v[180:183], v51 offset0:8 offset1:9
	ds_read2st64_b64 v[184:187], v51 offset0:10 offset1:11
	ds_read2st64_b64 v[188:191], v51 offset0:12 offset1:13
	ds_read2st64_b64 v[192:195], v51 offset0:14 offset1:15
	ds_read2st64_b64 v[196:199], v51 offset0:16 offset1:17
	ds_read2st64_b64 v[200:203], v51 offset0:18 offset1:19
	ds_read2st64_b64 v[204:207], v51 offset0:20 offset1:21
	ds_read2st64_b64 v[208:211], v51 offset0:22 offset1:23
	v_xor_b32_e32 v42, 0x80000000, v65
	v_mov_b32_e32 v43, v64
	v_pk_mul_f32 v[42:43], v[52:53], v[42:43] op_sel_hi:[0,1]
	v_pk_fma_f32 v[42:43], v[50:51], v[64:65], v[42:43] op_sel_hi:[0,1,1]
	s_waitcnt lgkmcnt(7)
	v_pk_add_f32 v[30:31], v[180:181], v[42:43]
	s_nop 0
	v_xor_b32_e32 v42, 0x80000000, v31
	v_mov_b32_e32 v43, v30
	v_pk_mul_f32 v[42:43], v[52:53], v[42:43] op_sel_hi:[0,1]
	v_pk_fma_f32 v[30:31], v[50:51], v[30:31], v[42:43] op_sel_hi:[0,1,1]
	v_pk_add_f32 v[42:43], v[182:183], v[30:31]
	v_xor_b32_e32 v44, 0x80000000, v43
	v_mov_b32_e32 v45, v42
	v_pk_mul_f32 v[44:45], v[52:53], v[44:45] op_sel_hi:[0,1]
	v_pk_fma_f32 v[42:43], v[50:51], v[42:43], v[44:45] op_sel_hi:[0,1,1]
	s_waitcnt lgkmcnt(6)
	v_pk_add_f32 v[30:31], v[184:185], v[42:43]
	s_nop 0
	v_xor_b32_e32 v42, 0x80000000, v31
	v_mov_b32_e32 v43, v30
	v_pk_mul_f32 v[42:43], v[52:53], v[42:43] op_sel_hi:[0,1]
	v_pk_fma_f32 v[30:31], v[50:51], v[30:31], v[42:43] op_sel_hi:[0,1,1]
	v_pk_add_f32 v[42:43], v[186:187], v[30:31]
	v_xor_b32_e32 v44, 0x80000000, v43
	v_mov_b32_e32 v45, v42
	v_pk_mul_f32 v[44:45], v[52:53], v[44:45] op_sel_hi:[0,1]
	v_pk_fma_f32 v[42:43], v[50:51], v[42:43], v[44:45] op_sel_hi:[0,1,1]
	s_waitcnt lgkmcnt(5)
	v_pk_add_f32 v[30:31], v[188:189], v[42:43]
	s_nop 0
	v_xor_b32_e32 v42, 0x80000000, v31
	v_mov_b32_e32 v43, v30
	v_pk_mul_f32 v[42:43], v[52:53], v[42:43] op_sel_hi:[0,1]
	v_pk_fma_f32 v[30:31], v[50:51], v[30:31], v[42:43] op_sel_hi:[0,1,1]
	v_pk_add_f32 v[42:43], v[190:191], v[30:31]
	v_xor_b32_e32 v44, 0x80000000, v43
	v_mov_b32_e32 v45, v42
	v_pk_mul_f32 v[44:45], v[52:53], v[44:45] op_sel_hi:[0,1]
	v_pk_fma_f32 v[42:43], v[50:51], v[42:43], v[44:45] op_sel_hi:[0,1,1]
	s_waitcnt lgkmcnt(4)
; __device__ __forceinline__ void s5_bu16(const S5Frag& f, const bf16x8 uf, float* buL, int lane) {
;     const int jj = lane & 15, quad = lane >> 4;
; #pragma unroll
;     for (int nt = 0; nt < 4; ++nt) {
;         const f32x4 z = (f32x4){0.f, 0.f, 0.f, 0.f};
;         const f32x4 dre = __builtin_amdgcn_mfma_f32_16x16x32_bf16(uf, f.bfr[nt], z, 0, 0, 0);
;         const f32x4 dim = __builtin_amdgcn_mfma_f32_16x16x32_bf16(uf, f.bfr[nt + 4], z, 0, 0, 0);
; #pragma unroll
;         for (int r = 0; r < 4; ++r) *(f32x2*)(buL + ((4 * quad + r) * 64 + 16 * nt + jj) * 2) = (f32x2){dre[r], dim[r]};
;     }
; }
; __device__ __forceinline__ void s5_pass1_item(PP p, unsigned char* shm, int item, int l) {
;     ...
; #pragma unroll
;     for (int sc = 0; sc < 4; ++sc) {
;         s5_bu16(f, uf[sc], buL, lane);
;         __syncthreads();
; #pragma unroll
;         for (int t = 0; t < 16; ++t) s5_rec(q, *(const f32x2*)(buL + (t * 64 + lane) * 2), x);
;         __syncthreads();
	v_pk_add_f32 v[30:31], v[192:193], v[42:43]
	s_nop 0
	v_xor_b32_e32 v42, 0x80000000, v31
	v_mov_b32_e32 v43, v30
	v_pk_mul_f32 v[42:43], v[52:53], v[42:43] op_sel_hi:[0,1]
	v_pk_fma_f32 v[30:31], v[50:51], v[30:31], v[42:43] op_sel_hi:[0,1,1]
	v_pk_add_f32 v[42:43], v[194:195], v[30:31]
	v_xor_b32_e32 v44, 0x80000000, v43
	v_mov_b32_e32 v45, v42
	v_pk_mul_f32 v[44:45], v[52:53], v[44:45] op_sel_hi:[0,1]
	v_pk_fma_f32 v[42:43], v[50:51], v[42:43], v[44:45] op_sel_hi:[0,1,1]
	s_waitcnt lgkmcnt(3)
	v_pk_add_f32 v[30:31], v[196:197], v[42:43]
	s_nop 0
	v_xor_b32_e32 v42, 0x80000000, v31
	v_mov_b32_e32 v43, v30
	v_pk_mul_f32 v[42:43], v[52:53], v[42:43] op_sel_hi:[0,1]
	v_pk_fma_f32 v[30:31], v[50:51], v[30:31], v[42:43] op_sel_hi:[0,1,1]
	v_pk_add_f32 v[42:43], v[198:199], v[30:31]
	v_xor_b32_e32 v44, 0x80000000, v43
	v_mov_b32_e32 v45, v42
	v_pk_mul_f32 v[44:45], v[52:53], v[44:45] op_sel_hi:[0,1]
	v_pk_fma_f32 v[42:43], v[50:51], v[42:43], v[44:45] op_sel_hi:[0,1,1]
	s_waitcnt lgkmcnt(2)
	v_pk_add_f32 v[30:31], v[200:201], v[42:43]
	s_nop 0
	v_xor_b32_e32 v42, 0x80000000, v31
	v_mov_b32_e32 v43, v30
	v_pk_mul_f32 v[42:43], v[52:53], v[42:43] op_sel_hi:[0,1]
	v_pk_fma_f32 v[30:31], v[50:51], v[30:31], v[42:43] op_sel_hi:[0,1,1]
	v_pk_add_f32 v[42:43], v[202:203], v[30:31]
	v_xor_b32_e32 v44, 0x80000000, v43
	v_mov_b32_e32 v45, v42
	v_pk_mul_f32 v[44:45], v[52:53], v[44:45] op_sel_hi:[0,1]
	v_pk_fma_f32 v[42:43], v[50:51], v[42:43], v[44:45] op_sel_hi:[0,1,1]
	s_waitcnt lgkmcnt(1)
	v_pk_add_f32 v[30:31], v[204:205], v[42:43]
	s_nop 0
	v_xor_b32_e32 v42, 0x80000000, v31
	v_mov_b32_e32 v43, v30
	v_pk_mul_f32 v[42:43], v[52:53], v[42:43] op_sel_hi:[0,1]
	v_pk_fma_f32 v[30:31], v[50:51], v[30:31], v[42:43] op_sel_hi:[0,1,1]
	v_pk_add_f32 v[42:43], v[206:207], v[30:31]
	v_xor_b32_e32 v44, 0x80000000, v43
	v_mov_b32_e32 v45, v42
	v_pk_mul_f32 v[44:45], v[52:53], v[44:45] op_sel_hi:[0,1]
	v_pk_fma_f32 v[42:43], v[50:51], v[42:43], v[44:45] op_sel_hi:[0,1,1]
	s_waitcnt lgkmcnt(0)
	v_pk_add_f32 v[30:31], v[208:209], v[42:43]
	s_nop 0
	v_xor_b32_e32 v42, 0x80000000, v31
	v_mov_b32_e32 v43, v30
	v_pk_mul_f32 v[42:43], v[52:53], v[42:43] op_sel_hi:[0,1]
	v_pk_fma_f32 v[30:31], v[50:51], v[30:31], v[42:43] op_sel_hi:[0,1,1]
	v_pk_add_f32 v[42:43], v[210:211], v[30:31]
	v_mfma_f32_16x16x32_bf16 v[30:33], v[2:5], v[38:41], 0
	v_mov_b32_e32 v38, v26
	v_mov_b32_e32 v40, v28
	s_nop 0
	s_nop 4
	v_mov_b32_e32 v39, v30
	v_mov_b32_e32 v30, v27
	v_mov_b32_e32 v41, v32
	v_mov_b32_e32 v32, v29
	v_mfma_f32_16x16x32_bf16 v[26:29], v[2:5], v[34:37], 0
	v_mov_b32_e32 v34, v14
	v_mov_b32_e32 v14, v16
	s_nop 5
	v_mov_b32_e32 v35, v26
	v_mov_b32_e32 v26, v15
	v_mov_b32_e32 v15, v28
	ds_write2_b64 v53, v[40:41], v[14:15] offset0:128 offset1:144
	v_mov_b32_e32 v28, v17
	v_mfma_f32_16x16x32_bf16 v[14:17], v[2:5], v[18:21], 0
	v_mov_b32_e32 v18, v6
	v_mov_b32_e32 v6, v8
	ds_write2_b64 v53, v[38:39], v[34:35] offset1:16
	s_nop 4
	v_mov_b32_e32 v19, v14
	v_mov_b32_e32 v14, v7
	v_mov_b32_e32 v7, v16
	ds_write2_b64 v53, v[6:7], v[32:33] offset0:160 offset1:192
	v_mov_b32_e32 v16, v9
	v_mfma_f32_16x16x32_bf16 v[6:9], v[2:5], v[10:13], 0
	ds_write2_b64 v53, v[18:19], v[30:31] offset0:32 offset1:64
	ds_write2_b64 v53, v[26:27], v[14:15] offset0:80 offset1:96
	ds_write2_b64 v53, v[28:29], v[16:17] offset0:208 offset1:224
	v_mfma_f32_16x16x32_bf16 v[2:5], v[2:5], v[22:25], 0
	s_nop 3
	v_mov_b32_e32 v10, v6
	s_nop 2
	v_mov_b32_e32 v11, v2
	v_mov_b32_e32 v2, v7
	ds_write2st64_b64 v55, v[10:11], v[2:3] offset0:8 offset1:9
	v_mov_b32_e32 v2, v8
	v_mov_b32_e32 v3, v4
	v_mov_b32_e32 v4, v9
	ds_write2st64_b64 v55, v[2:3], v[4:5] offset0:10 offset1:11
	s_waitcnt lgkmcnt(0)
	s_nop 0
	ds_read2st64_b64 v[180:183], v51 offset0:8 offset1:9
	ds_read2st64_b64 v[184:187], v51 offset0:10 offset1:11
	ds_read2st64_b64 v[188:191], v51 offset0:12 offset1:13
	ds_read2st64_b64 v[192:195], v51 offset0:14 offset1:15
	ds_read2st64_b64 v[196:199], v51 offset0:16 offset1:17
	ds_read2st64_b64 v[200:203], v51 offset0:18 offset1:19
	ds_read2st64_b64 v[204:207], v51 offset0:20 offset1:21
	ds_read2st64_b64 v[208:211], v51 offset0:22 offset1:23
	v_xor_b32_e32 v6, 0x80000000, v43
	v_mov_b32_e32 v7, v42
	v_pk_mul_f32 v[6:7], v[52:53], v[6:7] op_sel_hi:[0,1]
	v_pk_fma_f32 v[6:7], v[50:51], v[42:43], v[6:7] op_sel_hi:[0,1,1]
	s_waitcnt lgkmcnt(7)
; __device__ __forceinline__ void s5_pass1_item(PP p, unsigned char* shm, int item, int l) {
;     ...
; #pragma unroll
;         for (int t = 0; t < 16; ++t) s5_rec(q, *(const f32x2*)(buL + (t * 64 + lane) * 2), x);
;         __syncthreads();
;     }
;     *(f32x2*)((float*)(p->ws + WS_CARRY) + ((size_t)((b * 32 + g) * 32 + j) * 64 + lane) * 2) = x;
	v_pk_add_f32 v[2:3], v[180:181], v[6:7]
	s_nop 0
	v_xor_b32_e32 v6, 0x80000000, v3
	v_mov_b32_e32 v7, v2
	v_pk_mul_f32 v[6:7], v[52:53], v[6:7] op_sel_hi:[0,1]
	v_pk_fma_f32 v[2:3], v[50:51], v[2:3], v[6:7] op_sel_hi:[0,1,1]
	v_pk_add_f32 v[6:7], v[182:183], v[2:3]
	v_xor_b32_e32 v8, 0x80000000, v7
	v_mov_b32_e32 v9, v6
	v_pk_mul_f32 v[8:9], v[52:53], v[8:9] op_sel_hi:[0,1]
	v_pk_fma_f32 v[6:7], v[50:51], v[6:7], v[8:9] op_sel_hi:[0,1,1]
	s_waitcnt lgkmcnt(6)
	v_pk_add_f32 v[2:3], v[184:185], v[6:7]
	s_nop 0
	v_xor_b32_e32 v6, 0x80000000, v3
	v_mov_b32_e32 v7, v2
	v_pk_mul_f32 v[6:7], v[52:53], v[6:7] op_sel_hi:[0,1]
	v_pk_fma_f32 v[2:3], v[50:51], v[2:3], v[6:7] op_sel_hi:[0,1,1]
	v_pk_add_f32 v[6:7], v[186:187], v[2:3]
	v_xor_b32_e32 v8, 0x80000000, v7
	v_mov_b32_e32 v9, v6
	v_pk_mul_f32 v[8:9], v[52:53], v[8:9] op_sel_hi:[0,1]
	v_pk_fma_f32 v[6:7], v[50:51], v[6:7], v[8:9] op_sel_hi:[0,1,1]
	s_waitcnt lgkmcnt(5)
	v_pk_add_f32 v[2:3], v[188:189], v[6:7]
	s_nop 0
	v_xor_b32_e32 v6, 0x80000000, v3
	v_mov_b32_e32 v7, v2
	v_pk_mul_f32 v[6:7], v[52:53], v[6:7] op_sel_hi:[0,1]
	v_pk_fma_f32 v[2:3], v[50:51], v[2:3], v[6:7] op_sel_hi:[0,1,1]
	v_pk_add_f32 v[6:7], v[190:191], v[2:3]
	v_xor_b32_e32 v8, 0x80000000, v7
	v_mov_b32_e32 v9, v6
	v_pk_mul_f32 v[8:9], v[52:53], v[8:9] op_sel_hi:[0,1]
	v_pk_fma_f32 v[6:7], v[50:51], v[6:7], v[8:9] op_sel_hi:[0,1,1]
	s_waitcnt lgkmcnt(4)
	v_pk_add_f32 v[2:3], v[192:193], v[6:7]
	s_nop 0
	v_xor_b32_e32 v6, 0x80000000, v3
	v_mov_b32_e32 v7, v2
	v_pk_mul_f32 v[6:7], v[52:53], v[6:7] op_sel_hi:[0,1]
	v_pk_fma_f32 v[2:3], v[50:51], v[2:3], v[6:7] op_sel_hi:[0,1,1]
	v_pk_add_f32 v[6:7], v[194:195], v[2:3]
	v_xor_b32_e32 v8, 0x80000000, v7
	v_mov_b32_e32 v9, v6
	v_pk_mul_f32 v[8:9], v[52:53], v[8:9] op_sel_hi:[0,1]
	v_pk_fma_f32 v[6:7], v[50:51], v[6:7], v[8:9] op_sel_hi:[0,1,1]
	s_waitcnt lgkmcnt(3)
	v_pk_add_f32 v[2:3], v[196:197], v[6:7]
	s_nop 0
	v_xor_b32_e32 v6, 0x80000000, v3
	v_mov_b32_e32 v7, v2
	v_pk_mul_f32 v[6:7], v[52:53], v[6:7] op_sel_hi:[0,1]
	v_pk_fma_f32 v[2:3], v[50:51], v[2:3], v[6:7] op_sel_hi:[0,1,1]
	v_pk_add_f32 v[6:7], v[198:199], v[2:3]
	v_xor_b32_e32 v8, 0x80000000, v7
	v_mov_b32_e32 v9, v6
	v_pk_mul_f32 v[8:9], v[52:53], v[8:9] op_sel_hi:[0,1]
	v_pk_fma_f32 v[6:7], v[50:51], v[6:7], v[8:9] op_sel_hi:[0,1,1]
	s_waitcnt lgkmcnt(2)
	v_pk_add_f32 v[2:3], v[200:201], v[6:7]
	s_nop 0
	v_xor_b32_e32 v6, 0x80000000, v3
	v_mov_b32_e32 v7, v2
	v_pk_mul_f32 v[6:7], v[52:53], v[6:7] op_sel_hi:[0,1]
	v_pk_fma_f32 v[2:3], v[50:51], v[2:3], v[6:7] op_sel_hi:[0,1,1]
	v_pk_add_f32 v[6:7], v[202:203], v[2:3]
	v_xor_b32_e32 v8, 0x80000000, v7
	v_mov_b32_e32 v9, v6
	v_pk_mul_f32 v[8:9], v[52:53], v[8:9] op_sel_hi:[0,1]
	v_pk_fma_f32 v[6:7], v[50:51], v[6:7], v[8:9] op_sel_hi:[0,1,1]
	s_waitcnt lgkmcnt(1)
	v_pk_add_f32 v[2:3], v[204:205], v[6:7]
	s_nop 0
	v_xor_b32_e32 v6, 0x80000000, v3
	v_mov_b32_e32 v7, v2
	v_pk_mul_f32 v[6:7], v[52:53], v[6:7] op_sel_hi:[0,1]
	v_pk_fma_f32 v[2:3], v[50:51], v[2:3], v[6:7] op_sel_hi:[0,1,1]
	v_pk_add_f32 v[6:7], v[206:207], v[2:3]
	v_xor_b32_e32 v8, 0x80000000, v7
	v_mov_b32_e32 v9, v6
	v_pk_mul_f32 v[8:9], v[52:53], v[8:9] op_sel_hi:[0,1]
	v_pk_fma_f32 v[6:7], v[50:51], v[6:7], v[8:9] op_sel_hi:[0,1,1]
	s_waitcnt lgkmcnt(0)
	v_pk_add_f32 v[2:3], v[208:209], v[6:7]
	s_nop 0
	v_xor_b32_e32 v6, 0x80000000, v3
	v_mov_b32_e32 v7, v2
	v_pk_mul_f32 v[6:7], v[52:53], v[6:7] op_sel_hi:[0,1]
	v_pk_fma_f32 v[2:3], v[50:51], v[2:3], v[6:7] op_sel_hi:[0,1,1]
	v_pk_add_f32 v[2:3], v[210:211], v[2:3]
	v_add_u32_e32 v4, s3, v54
	v_ashrrev_i32_e32 v5, 31, v4
	v_lshlrev_b64 v[4:5], 9, v[4:5]
	v_lshl_add_u64 v[4:5], s[12:13], 0, v[4:5]
	v_lshl_add_u64 v[4:5], v[4:5], 0, v[0:1]
	v_add_co_u32_e32 v4, vcc, 0x31ac0000, v4
	s_barrier
	s_nop 0
	v_addc_co_u32_e32 v5, vcc, 0, v5, vcc
	global_store_dwordx2 v[4:5], v[2:3], off

; __device__ __forceinline__ void s5_pass2_item(PP p, unsigned char* shm, int item, int l) {
;     ...
;     float cmr[32];
;     { const float* src = ((quad < 2) ? p->in[11] : p->in[12]) + ((size_t)(l * 32 + g) * 16 + cc) * 64 + (quad & 1) * 32;
;       const float sgn = (quad < 2) ? 1.0f : -1.0f;
; #pragma unroll
;       for (int i = 0; i < 8; ++i) { const f32x4 v = *(const f32x4*)(src + 4 * i); cmr[4 * i] = v[0] * sgn; cmr[4 * i + 1] = v[1] * sgn; cmr[4 * i + 2] = v[2] * sgn; cmr[4 * i + 3] = v[3] * sgn; } }
;     S5Lane q; s5_lane_params(p, l, g, lane, q);
;     const size_t row0 = (size_t)b * SEQ + j * 64;
;     bf16x8 uf[4];
; #pragma unroll
;     for (int sc = 0; sc < 4; ++sc) uf[sc] = s5_ufrag(proj, row0 + sc * 16, g, lane);
;     s5_write_bbl(q, bbL, lane);
;     float pr = q.ar, pi = q.ai;
; #pragma unroll
;     for (int s = 0; s < 6; ++s) { const float nr = pr * pr - pi * pi, ni = 2.f * pr * pi; pr = nr; pi = ni; }
;     f32x2 x = (f32x2){0.f, 0.f};
;     const f32x2* carry = (const f32x2*)((const float*)(p->ws + WS_CARRY) + ((size_t)((b * 32 + g) * 32) * 64 + lane) * 2);
;     for (int i0 = 0; i0 < j; i0 += 8) {
;         f32x2 sv[8];
; #pragma unroll
;         for (int e = 0; e < 8; ++e) sv[e] = (i0 + e < j) ? carry[(size_t)(i0 + e) * 64] : (f32x2){0.f, 0.f};
; #pragma unroll
;         for (int e = 0; e < 8; ++e) if (i0 + e < j) { const f32x2 rot = (f32x2){-x.y, x.x}; x = (x * pr + rot * pi) + sv[e]; }
;     }
;     __syncthreads();
;     S5Frag f; s5_load_frags(bbL, f, lane);
;     const float dsk = p->in[13][(size_t)l * 512 + g * 16 + cc];
;     bf16_t* Gout = (bf16_t*)(p->ws + WS_GPH);
;     for (int sc = 0; sc < 4; ++sc) {
;         s5_bu16(f, uf[sc], buL, lane);
;         __syncthreads();
; #pragma unroll
;         for (int t = 0; t < 16; ++t) { s5_rec(q, *(const f32x2*)(buL + (t * 64 + lane) * 2), x); xs[t * 132 + lane] = x.x; xs[t * 132 + 64 + lane] = x.y; }
.LBB0_679:
	s_or_b64 exec, exec, s[2:3]
	s_movk_i32 s2, 0x2100
	v_mul_lo_u32 v0, v93, s2
	s_add_i32 s2, 0, 0x11000
	v_add_u32_e32 v102, s2, v0
	s_load_dwordx2 s[2:3], s[12:13], 0x68
	v_lshl_add_u32 v0, v93, 13, 0
	v_mul_f32_e32 v77, v77, v97
	v_mul_f32_e32 v76, v76, v97
	v_mul_f32_e32 v75, v75, v97
	s_waitcnt lgkmcnt(0)
	s_add_u32 s12, s2, s18
	s_addc_u32 s13, s3, 0
	s_lshl_b64 s[2:3], s[34:35], 2
	s_add_u32 s2, s12, s2
	v_mul_f32_e32 v74, v74, v97
	v_mul_f32_e32 v73, v73, v97
	v_mul_f32_e32 v72, v72, v97
	v_mul_f32_e32 v71, v71, v97
	v_mul_f32_e32 v70, v70, v97
	v_mul_f32_e32 v69, v69, v97
	v_mul_f32_e32 v68, v68, v97
	v_mul_f32_e32 v67, v67, v97
	v_mul_f32_e32 v66, v66, v97
	v_mul_f32_e32 v65, v65, v97
	v_mul_f32_e32 v64, v64, v97
	v_mul_f32_e32 v63, v63, v97
	v_mul_f32_e32 v62, v62, v97
	v_mul_f32_e32 v61, v61, v97
	v_mul_f32_e32 v60, v60, v97
	v_mul_f32_e32 v59, v59, v97
	v_mul_f32_e32 v58, v58, v97
	v_mul_f32_e32 v57, v57, v97
	v_mul_f32_e32 v56, v56, v97
	v_mul_f32_e32 v55, v55, v97
	v_mul_f32_e32 v85, v54, v97
	v_mul_f32_e32 v88, v53, v97
	v_mul_f32_e32 v91, v52, v97
	v_mul_f32_e32 v92, v51, v97
	v_mul_f32_e32 v93, v50, v97
	v_mul_f32_e32 v94, v49, v97
	v_mul_f32_e32 v95, v48, v97
	v_mul_f32_e32 v96, v47, v97
	v_mul_f32_e32 v97, v46, v97
	s_addc_u32 s3, s13, s3
	v_lshlrev_b32_e32 v46, 2, v100
	global_load_dword v54, v46, s[2:3]
	v_and_b32_e32 v46, 0x600, v99
	v_lshl_add_u32 v46, v46, 2, v0
	v_and_b32_e32 v47, 0x78, v90
	v_add_u32_e32 v108, v46, v47
	v_or_b32_e32 v47, 0x180, v90
	v_add_u32_e32 v99, v46, v47
	v_mul_u32_u24_e32 v46, 0x210, v100
	v_lshlrev_b32_e32 v47, 2, v101
	v_add_u32_e32 v90, v0, v90
	v_mov_b32_e32 v0, v89
	v_lshl_add_u32 v98, v98, 2, v102
	v_add3_u32 v89, v102, v46, v47
	v_or_b32_e32 v50, s34, v100
	v_mfma_f32_16x16x32_bf16 v[46:49], v[78:81], v[26:29], 0
	v_add_u32_e32 v108, 0x1000, v108
	v_lshl_or_b32 v82, v109, 2, v82
	v_mov_b32_e32 v51, s35
	v_mfma_f32_16x16x32_bf16 v[100:103], v[78:81], v[34:37], 0
	s_add_u32 s28, s28, 0x21600000
	s_nop 2
	v_mov_b32_e32 v52, v46
	v_mov_b32_e32 v110, v48
	v_mfma_f32_16x16x32_bf16 v[104:107], v[78:81], v[30:33], 0
	s_addc_u32 s29, s29, 0
	v_mov_b32_e32 v53, v100
	v_mov_b32_e32 v100, v47
	v_mov_b32_e32 v111, v102
	v_mov_b32_e32 v102, v49
	v_mfma_f32_16x16x32_bf16 v[46:49], v[78:81], v[22:25], 0
	s_nop 1
	v_mov_b32_e32 v113, v104
	s_xor_b32 s14, s14, 3
	s_add_i32 s14, s14, s66
	s_cmpk_gt_i32 s14, 0x1ff
	s_nop 2
	v_mov_b32_e32 v112, v46
	v_mov_b32_e32 v104, v47
	v_mov_b32_e32 v46, v48
	v_mov_b32_e32 v47, v106
	ds_write2_b64 v108, v[52:53], v[112:113] offset1:16
	ds_write2_b64 v108, v[110:111], v[46:47] offset0:128 offset1:144
	v_mov_b32_e32 v106, v49
	v_mfma_f32_16x16x32_bf16 v[46:49], v[78:81], v[18:21], 0
	v_mfma_f32_16x16x32_bf16 v[110:113], v[78:81], v[14:17], 0
	s_nop 6
	v_mov_b32_e32 v52, v46
	v_mov_b32_e32 v53, v110
	v_mov_b32_e32 v110, v47
	v_mov_b32_e32 v46, v48
	v_mov_b32_e32 v47, v112
	ds_write2_b64 v108, v[46:47], v[102:103] offset0:160 offset1:192
	v_mov_b32_e32 v112, v49
	v_mfma_f32_16x16x32_bf16 v[46:49], v[78:81], v[10:13], 0
	ds_write2_b64 v108, v[52:53], v[100:101] offset0:32 offset1:64
	ds_write2_b64 v108, v[104:105], v[110:111] offset0:80 offset1:96
	ds_write2_b64 v108, v[106:107], v[112:113] offset0:208 offset1:224
	v_mfma_f32_16x16x32_bf16 v[78:81], v[78:81], v[6:9], 0
	v_add_u32_e32 v100, 0x80, v98
	s_nop 2
	v_mov_b32_e32 v52, v46
	v_mov_b32_e32 v46, v48
	v_xor_b32_e32 v48, 0x80000000, v87
	v_add_u32_e32 v101, 0x90, v98
	v_mov_b32_e32 v53, v78
	v_mov_b32_e32 v78, v47
	v_mov_b32_e32 v47, v80
	v_mov_b32_e32 v80, v49
	ds_write2st64_b64 v99, v[52:53], v[78:79] offset0:8 offset1:9
	ds_write2st64_b64 v99, v[46:47], v[80:81] offset0:10 offset1:11
	s_waitcnt lgkmcnt(0)
	s_nop 0
	ds_read_b64 v[140:141], v90 offset:4096
	ds_read_b64 v[142:143], v90 offset:4608
	ds_read_b64 v[144:145], v90 offset:5120
	ds_read_b64 v[146:147], v90 offset:5632
	ds_read_b64 v[148:149], v90 offset:6144
	ds_read_b64 v[150:151], v90 offset:6656
	ds_read_b64 v[152:153], v90 offset:7168
	ds_read_b64 v[154:155], v90 offset:7680
	v_mov_b32_e32 v49, v86
	v_pk_mul_f32 v[48:49], v[0:1], v[48:49] op_sel_hi:[0,1]
	v_pk_fma_f32 v[48:49], v[84:85], v[86:87], v[48:49] op_sel_hi:[0,1,1]
	v_add_u32_e32 v78, 32, v98
	s_waitcnt lgkmcnt(7)
	v_pk_add_f32 v[46:47], v[48:49], v[140:141]
	ds_write2st64_b32 v98, v46, v47 offset1:1
	v_xor_b32_e32 v52, 0x80000000, v47
	v_mov_b32_e32 v53, v46
	v_pk_mul_f32 v[52:53], v[0:1], v[52:53] op_sel_hi:[0,1]
	v_pk_fma_f32 v[46:47], v[84:85], v[46:47], v[52:53] op_sel_hi:[0,1,1]
	s_waitcnt lgkmcnt(7)
	v_pk_add_f32 v[46:47], v[142:143], v[46:47]
	ds_write2_b32 v98, v46, v47 offset0:132 offset1:196
	v_xor_b32_e32 v52, 0x80000000, v47
	v_mov_b32_e32 v53, v46
	v_pk_mul_f32 v[52:53], v[0:1], v[52:53] op_sel_hi:[0,1]
	v_pk_fma_f32 v[46:47], v[84:85], v[46:47], v[52:53] op_sel_hi:[0,1,1]
	s_waitcnt lgkmcnt(7)
	v_pk_add_f32 v[46:47], v[144:145], v[46:47]
	ds_write2st64_b32 v78, v46, v47 offset0:4 offset1:5
	v_xor_b32_e32 v52, 0x80000000, v47
	v_mov_b32_e32 v53, v46
	v_pk_mul_f32 v[52:53], v[0:1], v[52:53] op_sel_hi:[0,1]
	v_pk_fma_f32 v[46:47], v[84:85], v[46:47], v[52:53] op_sel_hi:[0,1,1]
	s_waitcnt lgkmcnt(7)
	v_pk_add_f32 v[46:47], v[146:147], v[46:47]
	v_add_u32_e32 v79, 48, v98
	ds_write2st64_b32 v79, v46, v47 offset0:6 offset1:7
	v_xor_b32_e32 v52, 0x80000000, v47
	v_mov_b32_e32 v53, v46
	v_pk_mul_f32 v[52:53], v[0:1], v[52:53] op_sel_hi:[0,1]
	v_pk_fma_f32 v[46:47], v[84:85], v[46:47], v[52:53] op_sel_hi:[0,1,1]
	s_waitcnt lgkmcnt(7)
; __device__ __forceinline__ float bf2f(bf16_t v) { return __uint_as_float(((unsigned)v) << 16); }
; __device__ __forceinline__ void s5_pass2_item(PP p, unsigned char* shm, int item, int l) {
;     ...
;     for (int sc = 0; sc < 4; ++sc) {
;         s5_bu16(f, uf[sc], buL, lane);
;         __syncthreads();
; #pragma unroll
;         for (int t = 0; t < 16; ++t) { s5_rec(q, *(const f32x2*)(buL + (t * 64 + lane) * 2), x); xs[t * 132 + lane] = x.x; xs[t * 132 + 64 + lane] = x.y; }
;         __syncthreads();
;         f32x4 y0 = (f32x4){0.f, 0.f, 0.f, 0.f}, y1 = y0;
;         const f32x4* xrow = (const f32x4*)(xs + cc * 132 + quad * 32);
; #pragma unroll
;         for (int i = 0; i < 8; ++i) { const f32x4 xv = xrow[i];
;             y0 = __builtin_amdgcn_mfma_f32_16x16x4f32(xv[0], cmr[4 * i + 0], y0, 0, 0, 0);
;             y1 = __builtin_amdgcn_mfma_f32_16x16x4f32(xv[1], cmr[4 * i + 1], y1, 0, 0, 0);
;             y0 = __builtin_amdgcn_mfma_f32_16x16x4f32(xv[2], cmr[4 * i + 2], y0, 0, 0, 0);
;             y1 = __builtin_amdgcn_mfma_f32_16x16x4f32(xv[3], cmr[4 * i + 3], y1, 0, 0, 0); }
;         const f32x4 y = y0 + y1;
; #pragma unroll
;         for (int r = 0; r < 4; ++r) { const int tl = sc * 16 + quad * 4 + r;
;             const float v = y[r] + dsk * bf2f(proj[PJ_UA + (row0 + tl) * 512 + g * 16 + cc]);
	v_pk_add_f32 v[46:47], v[148:149], v[46:47]
	v_add_u32_e32 v80, 64, v98
	ds_write2st64_b32 v80, v46, v47 offset0:8 offset1:9
	v_xor_b32_e32 v52, 0x80000000, v47
	v_mov_b32_e32 v53, v46
	v_pk_mul_f32 v[52:53], v[0:1], v[52:53] op_sel_hi:[0,1]
	v_pk_fma_f32 v[46:47], v[84:85], v[46:47], v[52:53] op_sel_hi:[0,1,1]
	s_waitcnt lgkmcnt(7)
	v_pk_add_f32 v[46:47], v[150:151], v[46:47]
	v_add_u32_e32 v81, 0x50, v98
	ds_write2st64_b32 v81, v46, v47 offset0:10 offset1:11
	v_xor_b32_e32 v52, 0x80000000, v47
	v_mov_b32_e32 v53, v46
	v_pk_mul_f32 v[52:53], v[0:1], v[52:53] op_sel_hi:[0,1]
	v_pk_fma_f32 v[46:47], v[84:85], v[46:47], v[52:53] op_sel_hi:[0,1,1]
	s_waitcnt lgkmcnt(7)
	v_pk_add_f32 v[46:47], v[152:153], v[46:47]
	v_add_u32_e32 v86, 0x60, v98
	ds_write2st64_b32 v86, v46, v47 offset0:12 offset1:13
	v_xor_b32_e32 v52, 0x80000000, v47
	v_mov_b32_e32 v53, v46
	v_pk_mul_f32 v[52:53], v[0:1], v[52:53] op_sel_hi:[0,1]
	v_pk_fma_f32 v[46:47], v[84:85], v[46:47], v[52:53] op_sel_hi:[0,1,1]
	s_waitcnt lgkmcnt(7)
	v_pk_add_f32 v[46:47], v[154:155], v[46:47]
	v_add_u32_e32 v87, 0x70, v98
	ds_write2st64_b32 v87, v46, v47 offset0:14 offset1:15
	ds_read_b64 v[140:141], v90 offset:8192
	ds_read_b64 v[142:143], v90 offset:8704
	ds_read_b64 v[144:145], v90 offset:9216
	ds_read_b64 v[146:147], v90 offset:9728
	ds_read_b64 v[148:149], v90 offset:10240
	ds_read_b64 v[150:151], v90 offset:10752
	ds_read_b64 v[152:153], v90 offset:11264
	ds_read_b64 v[154:155], v90 offset:11776
	v_xor_b32_e32 v52, 0x80000000, v47
	v_mov_b32_e32 v53, v46
	v_pk_mul_f32 v[52:53], v[0:1], v[52:53] op_sel_hi:[0,1]
	v_pk_fma_f32 v[46:47], v[84:85], v[46:47], v[52:53] op_sel_hi:[0,1,1]
	s_waitcnt lgkmcnt(7)
	v_pk_add_f32 v[46:47], v[140:141], v[46:47]
	ds_write2st64_b32 v100, v46, v47 offset0:16 offset1:17
	v_xor_b32_e32 v52, 0x80000000, v47
	v_mov_b32_e32 v53, v46
	v_pk_mul_f32 v[52:53], v[0:1], v[52:53] op_sel_hi:[0,1]
	v_pk_fma_f32 v[46:47], v[84:85], v[46:47], v[52:53] op_sel_hi:[0,1,1]
	s_waitcnt lgkmcnt(7)
	v_pk_add_f32 v[46:47], v[142:143], v[46:47]
	ds_write2st64_b32 v101, v46, v47 offset0:18 offset1:19
	v_xor_b32_e32 v52, 0x80000000, v47
	v_mov_b32_e32 v53, v46
	v_pk_mul_f32 v[52:53], v[0:1], v[52:53] op_sel_hi:[0,1]
	v_pk_fma_f32 v[46:47], v[84:85], v[46:47], v[52:53] op_sel_hi:[0,1,1]
	s_waitcnt lgkmcnt(7)
	v_pk_add_f32 v[46:47], v[144:145], v[46:47]
	v_add_u32_e32 v102, 0xa0, v98
	ds_write2st64_b32 v102, v46, v47 offset0:20 offset1:21
	v_xor_b32_e32 v52, 0x80000000, v47
	v_mov_b32_e32 v53, v46
	v_pk_mul_f32 v[52:53], v[0:1], v[52:53] op_sel_hi:[0,1]
	v_pk_fma_f32 v[46:47], v[84:85], v[46:47], v[52:53] op_sel_hi:[0,1,1]
	s_waitcnt lgkmcnt(7)
	v_pk_add_f32 v[46:47], v[146:147], v[46:47]
	v_add_u32_e32 v103, 0xb0, v98
	ds_write2st64_b32 v103, v46, v47 offset0:22 offset1:23
	v_xor_b32_e32 v52, 0x80000000, v47
	v_mov_b32_e32 v53, v46
	v_pk_mul_f32 v[52:53], v[0:1], v[52:53] op_sel_hi:[0,1]
	v_pk_fma_f32 v[46:47], v[84:85], v[46:47], v[52:53] op_sel_hi:[0,1,1]
	s_waitcnt lgkmcnt(7)
	v_pk_add_f32 v[46:47], v[148:149], v[46:47]
	v_add_u32_e32 v104, 0xc0, v98
	ds_write2st64_b32 v104, v46, v47 offset0:24 offset1:25
	v_xor_b32_e32 v52, 0x80000000, v47
	v_mov_b32_e32 v53, v46
	v_pk_mul_f32 v[52:53], v[0:1], v[52:53] op_sel_hi:[0,1]
	v_pk_fma_f32 v[46:47], v[84:85], v[46:47], v[52:53] op_sel_hi:[0,1,1]
	s_waitcnt lgkmcnt(7)
	v_pk_add_f32 v[46:47], v[150:151], v[46:47]
	v_add_u32_e32 v105, 0xd0, v98
	ds_write2st64_b32 v105, v46, v47 offset0:26 offset1:27
	v_xor_b32_e32 v52, 0x80000000, v47
	v_mov_b32_e32 v53, v46
	v_pk_mul_f32 v[52:53], v[0:1], v[52:53] op_sel_hi:[0,1]
	v_pk_fma_f32 v[46:47], v[84:85], v[46:47], v[52:53] op_sel_hi:[0,1,1]
	s_waitcnt lgkmcnt(7)
	v_pk_add_f32 v[46:47], v[152:153], v[46:47]
	v_add_u32_e32 v106, 0xe0, v98
	ds_write2st64_b32 v106, v46, v47 offset0:28 offset1:29
	v_xor_b32_e32 v52, 0x80000000, v47
	v_mov_b32_e32 v53, v46
	v_pk_mul_f32 v[52:53], v[0:1], v[52:53] op_sel_hi:[0,1]
	v_pk_fma_f32 v[46:47], v[84:85], v[46:47], v[52:53] op_sel_hi:[0,1,1]
	s_waitcnt lgkmcnt(7)
	v_pk_add_f32 v[52:53], v[154:155], v[46:47]
	v_add_u32_e32 v107, 0xf0, v98
	ds_write2st64_b32 v107, v52, v53 offset0:30 offset1:31
	s_waitcnt lgkmcnt(0)
	s_nop 0
	v_mov_b32_e32 v216, v82
	v_mov_b32_e32 v217, v83
	v_lshlrev_b64 v[216:217], 9, v[216:217]
	v_lshl_add_u64 v[216:217], v[216:217], 0, v[50:51]
	v_lshlrev_b64 v[216:217], 1, v[216:217]
	v_lshl_add_u64 v[216:217], s[8:9], 0, v[216:217]
	global_load_ushort v200, v[216:217], off
	global_load_ushort v201, v[216:217], off offset:1024
	global_load_ushort v202, v[216:217], off offset:2048
	global_load_ushort v203, v[216:217], off offset:3072
	ds_read_b128 v[46:49], v89
	ds_read_b128 v[110:113], v89 offset:16
	ds_read_b128 v[114:117], v89 offset:32
	ds_read_b128 v[118:121], v89 offset:48
	s_waitcnt lgkmcnt(3)
	v_mfma_f32_16x16x4_f32 v[122:125], v46, v97, 0
	v_mfma_f32_16x16x4_f32 v[126:129], v47, v96, 0
	v_mfma_f32_16x16x4_f32 v[122:125], v48, v95, v[122:125]
	v_mfma_f32_16x16x4_f32 v[46:49], v49, v94, v[126:129]
	s_waitcnt lgkmcnt(2)
	v_mfma_f32_16x16x4_f32 v[122:125], v110, v93, v[122:125]
	v_mfma_f32_16x16x4_f32 v[46:49], v111, v92, v[46:49]
	v_mfma_f32_16x16x4_f32 v[122:125], v112, v91, v[122:125]
	v_mfma_f32_16x16x4_f32 v[46:49], v113, v88, v[46:49]
	s_waitcnt lgkmcnt(1)
	v_mfma_f32_16x16x4_f32 v[110:113], v114, v85, v[122:125]
	v_mfma_f32_16x16x4_f32 v[46:49], v115, v55, v[46:49]
	v_mfma_f32_16x16x4_f32 v[110:113], v116, v56, v[110:113]
	v_mfma_f32_16x16x4_f32 v[46:49], v117, v57, v[46:49]
	ds_read_b128 v[114:117], v89 offset:64
	s_waitcnt lgkmcnt(1)
; __device__ __forceinline__ float bf2f(bf16_t v) { return __uint_as_float(((unsigned)v) << 16); }
; __device__ __forceinline__ bf16_t f2bf(float f) { unsigned u = __float_as_uint(f); u += 0x7FFFu + ((u >> 16) & 1u); return (bf16_t)(u >> 16); }
; __device__ __forceinline__ void s5_pass2_item(PP p, unsigned char* shm, int item, int l) {
;     ...
;         f32x4 y0 = (f32x4){0.f, 0.f, 0.f, 0.f}, y1 = y0;
;         const f32x4* xrow = (const f32x4*)(xs + cc * 132 + quad * 32);
; #pragma unroll
;         for (int i = 0; i < 8; ++i) { const f32x4 xv = xrow[i];
;             y0 = __builtin_amdgcn_mfma_f32_16x16x4f32(xv[0], cmr[4 * i + 0], y0, 0, 0, 0);
;             y1 = __builtin_amdgcn_mfma_f32_16x16x4f32(xv[1], cmr[4 * i + 1], y1, 0, 0, 0);
;             y0 = __builtin_amdgcn_mfma_f32_16x16x4f32(xv[2], cmr[4 * i + 2], y0, 0, 0, 0);
;             y1 = __builtin_amdgcn_mfma_f32_16x16x4f32(xv[3], cmr[4 * i + 3], y1, 0, 0, 0); }
;         const f32x4 y = y0 + y1;
; #pragma unroll
;         for (int r = 0; r < 4; ++r) { const int tl = sc * 16 + quad * 4 + r;
;             const float v = y[r] + dsk * bf2f(proj[PJ_UA + (row0 + tl) * 512 + g * 16 + cc]);
;             const float z = 0.7978845608028654f * (v + 0.044715f * v * v * v);
;             const float th = 1.0f - 2.0f / (__expf(2.0f * z) + 1.0f);
;             Gout[(row0 + tl) * 512 + g * 16 + cc] = f2bf(0.5f * v * (1.0f + th)); }
	v_mfma_f32_16x16x4_f32 v[110:113], v118, v58, v[110:113]
	v_mfma_f32_16x16x4_f32 v[46:49], v119, v59, v[46:49]
	v_mfma_f32_16x16x4_f32 v[110:113], v120, v60, v[110:113]
	v_mfma_f32_16x16x4_f32 v[46:49], v121, v61, v[46:49]
	s_waitcnt lgkmcnt(0)
	v_mfma_f32_16x16x4_f32 v[110:113], v114, v62, v[110:113]
	v_mfma_f32_16x16x4_f32 v[46:49], v115, v63, v[46:49]
	v_mfma_f32_16x16x4_f32 v[110:113], v116, v64, v[110:113]
	v_mfma_f32_16x16x4_f32 v[46:49], v117, v65, v[46:49]
	ds_read_b128 v[114:117], v89 offset:80
	s_waitcnt lgkmcnt(0)
	v_mfma_f32_16x16x4_f32 v[110:113], v114, v66, v[110:113]
	v_mfma_f32_16x16x4_f32 v[46:49], v115, v67, v[46:49]
	v_mfma_f32_16x16x4_f32 v[110:113], v116, v68, v[110:113]
	v_mfma_f32_16x16x4_f32 v[46:49], v117, v69, v[46:49]
	ds_read_b128 v[114:117], v89 offset:96
	s_waitcnt lgkmcnt(0)
	v_mfma_f32_16x16x4_f32 v[110:113], v114, v70, v[110:113]
	v_mfma_f32_16x16x4_f32 v[46:49], v115, v71, v[46:49]
	v_mfma_f32_16x16x4_f32 v[110:113], v116, v72, v[110:113]
	v_mfma_f32_16x16x4_f32 v[46:49], v117, v73, v[46:49]
	ds_read_b128 v[114:117], v89 offset:112
	s_waitcnt lgkmcnt(0)
	v_mfma_f32_16x16x4_f32 v[110:113], v114, v74, v[110:113]
	v_mfma_f32_16x16x4_f32 v[46:49], v115, v75, v[46:49]
	v_mfma_f32_16x16x4_f32 v[110:113], v116, v76, v[110:113]
	v_mfma_f32_16x16x4_f32 v[46:49], v117, v77, v[46:49]
	s_nop 9
	v_pk_add_f32 v[46:47], v[110:111], v[46:47]
	v_lshlrev_b64 v[110:111], 9, v[82:83]
	v_lshl_add_u64 v[110:111], v[110:111], 0, v[50:51]
	v_lshlrev_b64 v[110:111], 1, v[110:111]
	v_pk_add_f32 v[48:49], v[112:113], v[48:49]
	v_lshl_add_u64 v[112:113], s[8:9], 0, v[110:111]
	v_lshl_add_u64 v[110:111], s[28:29], 0, v[110:111]
	s_waitcnt vmcnt(3)
	v_lshlrev_b32_e32 v109, 16, v200
	v_fma_f32 v46, v54, v109, v46
	v_mul_f32_e32 v109, 0x3d372713, v46
	v_mul_f32_e32 v109, v46, v109
	v_fma_f32 v109, v46, v109, v46
	v_mul_f32_e32 v109, 0x3f4c422a, v109
	v_add_f32_e32 v109, v109, v109
	v_mul_f32_e32 v109, 0x3fb8aa3b, v109
	v_exp_f32_e32 v109, v109
	v_mul_f32_e32 v46, 0.5, v46
	v_add_f32_e32 v109, 1.0, v109
	v_div_scale_f32 v112, s[2:3], v109, v109, 2.0
	v_rcp_f32_e32 v113, v112
	s_nop 0
	v_fma_f32 v114, -v112, v113, 1.0
	v_fmac_f32_e32 v113, v114, v113
	v_div_scale_f32 v114, vcc, 2.0, v109, 2.0
	v_mul_f32_e32 v115, v114, v113
	v_fma_f32 v116, -v112, v115, v114
	v_fmac_f32_e32 v115, v116, v113
	v_fma_f32 v112, -v112, v115, v114
	v_div_fmas_f32 v112, v112, v113, v115
	v_div_fixup_f32 v109, v112, v109, 2.0
	v_sub_f32_e32 v109, 1.0, v109
	v_add_f32_e32 v109, 1.0, v109
	v_mul_f32_e32 v46, v46, v109
	v_bfe_u32 v109, v46, 16, 1
	v_add3_u32 v46, v46, v109, s31
	global_store_short_d16_hi v[110:111], v46, off
	v_or_b32_e32 v110, 1, v82
	v_mov_b32_e32 v111, v83
	v_lshlrev_b64 v[110:111], 9, v[110:111]
	v_lshl_add_u64 v[110:111], v[110:111], 0, v[50:51]
	v_lshlrev_b64 v[110:111], 1, v[110:111]
	v_lshl_add_u64 v[112:113], s[8:9], 0, v[110:111]
	s_waitcnt vmcnt(3)
	v_lshlrev_b32_e32 v46, 16, v201
	v_fmac_f32_e32 v47, v54, v46
	v_mul_f32_e32 v46, 0x3d372713, v47
	v_mul_f32_e32 v46, v47, v46
	v_fma_f32 v46, v47, v46, v47
	v_mul_f32_e32 v46, 0x3f4c422a, v46
	v_add_f32_e32 v46, v46, v46
	v_mul_f32_e32 v46, 0x3fb8aa3b, v46
	v_exp_f32_e32 v46, v46
	v_mul_f32_e32 v47, 0.5, v47
	v_add_f32_e32 v46, 1.0, v46
	v_div_scale_f32 v109, s[2:3], v46, v46, 2.0
	v_rcp_f32_e32 v112, v109
	s_nop 0
	v_fma_f32 v113, -v109, v112, 1.0
	v_fmac_f32_e32 v112, v113, v112
	v_div_scale_f32 v113, vcc, 2.0, v46, 2.0
	v_mul_f32_e32 v114, v113, v112
	v_fma_f32 v115, -v109, v114, v113
	v_fmac_f32_e32 v114, v115, v112
	v_fma_f32 v109, -v109, v114, v113
	v_div_fmas_f32 v109, v109, v112, v114
	v_div_fixup_f32 v46, v109, v46, 2.0
	v_sub_f32_e32 v46, 1.0, v46
	v_add_f32_e32 v46, 1.0, v46
	v_mul_f32_e32 v46, v47, v46
	v_bfe_u32 v47, v46, 16, 1
	v_add3_u32 v109, v46, v47, s31
	v_lshl_add_u64 v[46:47], s[28:29], 0, v[110:111]
	global_store_short_d16_hi v[46:47], v109, off
	v_or_b32_e32 v46, 2, v82
	v_mov_b32_e32 v47, v83
	v_lshlrev_b64 v[46:47], 9, v[46:47]
	v_lshl_add_u64 v[46:47], v[46:47], 0, v[50:51]
	v_lshlrev_b64 v[46:47], 1, v[46:47]
	v_lshl_add_u64 v[110:111], s[8:9], 0, v[46:47]
	v_lshl_add_u64 v[46:47], s[28:29], 0, v[46:47]
	s_waitcnt vmcnt(3)
	v_lshlrev_b32_e32 v109, 16, v202
	v_fma_f32 v48, v54, v109, v48
	v_mul_f32_e32 v109, 0x3d372713, v48
	v_mul_f32_e32 v109, v48, v109
	v_fma_f32 v109, v48, v109, v48
	v_mul_f32_e32 v109, 0x3f4c422a, v109
	v_add_f32_e32 v109, v109, v109
	v_mul_f32_e32 v109, 0x3fb8aa3b, v109
	v_exp_f32_e32 v109, v109
	v_mul_f32_e32 v48, 0.5, v48
	v_add_f32_e32 v109, 1.0, v109
	v_div_scale_f32 v110, s[2:3], v109, v109, 2.0
	v_rcp_f32_e32 v111, v110
	s_nop 0
	v_fma_f32 v112, -v110, v111, 1.0
	v_fmac_f32_e32 v111, v112, v111
	v_div_scale_f32 v112, vcc, 2.0, v109, 2.0
	v_mul_f32_e32 v113, v112, v111
	v_fma_f32 v114, -v110, v113, v112
	v_fmac_f32_e32 v113, v114, v111
	v_fma_f32 v110, -v110, v113, v112
	v_div_fmas_f32 v110, v110, v111, v113
	v_div_fixup_f32 v109, v110, v109, 2.0
	v_sub_f32_e32 v109, 1.0, v109
	v_add_f32_e32 v109, 1.0, v109
	v_mul_f32_e32 v48, v48, v109
	v_bfe_u32 v109, v48, 16, 1
	v_add3_u32 v48, v48, v109, s31
	global_store_short_d16_hi v[46:47], v48, off
	v_or_b32_e32 v46, 3, v82
	v_mov_b32_e32 v47, v83
	v_lshlrev_b64 v[46:47], 9, v[46:47]
	v_lshl_add_u64 v[46:47], v[46:47], 0, v[50:51]
	v_lshlrev_b64 v[46:47], 1, v[46:47]
	v_lshl_add_u64 v[110:111], s[8:9], 0, v[46:47]
	v_lshl_add_u64 v[46:47], s[28:29], 0, v[46:47]
	v_mfma_f32_16x16x32_bf16 v[114:117], v[42:45], v[30:33], 0
	s_waitcnt vmcnt(3)
; __device__ __forceinline__ float bf2f(bf16_t v) { return __uint_as_float(((unsigned)v) << 16); }
; __device__ __forceinline__ bf16_t f2bf(float f) { unsigned u = __float_as_uint(f); u += 0x7FFFu + ((u >> 16) & 1u); return (bf16_t)(u >> 16); }
; __device__ __forceinline__ void s5_pass2_item(PP p, unsigned char* shm, int item, int l) {
;     ...
;     for (int sc = 0; sc < 4; ++sc) {
;         s5_bu16(f, uf[sc], buL, lane);
;         __syncthreads();
; #pragma unroll
;         for (int t = 0; t < 16; ++t) { s5_rec(q, *(const f32x2*)(buL + (t * 64 + lane) * 2), x); xs[t * 132 + lane] = x.x; xs[t * 132 + 64 + lane] = x.y; }
;         __syncthreads();
;         f32x4 y0 = (f32x4){0.f, 0.f, 0.f, 0.f}, y1 = y0;
;         const f32x4* xrow = (const f32x4*)(xs + cc * 132 + quad * 32);
; #pragma unroll
;         for (int i = 0; i < 8; ++i) { const f32x4 xv = xrow[i];
;             y0 = __builtin_amdgcn_mfma_f32_16x16x4f32(xv[0], cmr[4 * i + 0], y0, 0, 0, 0);
;             y1 = __builtin_amdgcn_mfma_f32_16x16x4f32(xv[1], cmr[4 * i + 1], y1, 0, 0, 0);
;             y0 = __builtin_amdgcn_mfma_f32_16x16x4f32(xv[2], cmr[4 * i + 2], y0, 0, 0, 0);
;             y1 = __builtin_amdgcn_mfma_f32_16x16x4f32(xv[3], cmr[4 * i + 3], y1, 0, 0, 0); }
;         const f32x4 y = y0 + y1;
; #pragma unroll
;         for (int r = 0; r < 4; ++r) { const int tl = sc * 16 + quad * 4 + r;
;             const float v = y[r] + dsk * bf2f(proj[PJ_UA + (row0 + tl) * 512 + g * 16 + cc]);
;             const float z = 0.7978845608028654f * (v + 0.044715f * v * v * v);
;             const float th = 1.0f - 2.0f / (__expf(2.0f * z) + 1.0f);
;             Gout[(row0 + tl) * 512 + g * 16 + cc] = f2bf(0.5f * v * (1.0f + th)); }
;         __syncthreads();
	v_lshlrev_b32_e32 v48, 16, v203
	v_fmac_f32_e32 v49, v54, v48
	v_mul_f32_e32 v48, 0x3d372713, v49
	v_mul_f32_e32 v48, v49, v48
	v_fma_f32 v48, v49, v48, v49
	v_mul_f32_e32 v48, 0x3f4c422a, v48
	v_add_f32_e32 v48, v48, v48
	v_mul_f32_e32 v48, 0x3fb8aa3b, v48
	v_exp_f32_e32 v48, v48
	v_mul_f32_e32 v49, 0.5, v49
	v_mov_b32_e32 v123, v114
	v_add_f32_e32 v48, 1.0, v48
	v_div_scale_f32 v109, s[2:3], v48, v48, 2.0
	v_rcp_f32_e32 v110, v109
	s_nop 0
	v_fma_f32 v111, -v109, v110, 1.0
	v_fmac_f32_e32 v110, v111, v110
	v_div_scale_f32 v111, vcc, 2.0, v48, 2.0
	v_mul_f32_e32 v112, v111, v110
	v_fma_f32 v113, -v109, v112, v111
	v_fmac_f32_e32 v112, v113, v110
	v_fma_f32 v109, -v109, v112, v111
	v_div_fmas_f32 v109, v109, v110, v112
	v_div_fixup_f32 v48, v109, v48, 2.0
	v_sub_f32_e32 v48, 1.0, v48
	v_add_f32_e32 v48, 1.0, v48
	v_mul_f32_e32 v48, v49, v48
	v_bfe_u32 v49, v48, 16, 1
	v_add3_u32 v48, v48, v49, s31
	global_store_short_d16_hi v[46:47], v48, off
	v_mfma_f32_16x16x32_bf16 v[46:49], v[42:45], v[26:29], 0
	s_nop 0
	v_mfma_f32_16x16x32_bf16 v[110:113], v[42:45], v[34:37], 0
	s_nop 5
	v_mov_b32_e32 v118, v46
	s_nop 0
	v_mov_b32_e32 v119, v110
	v_mov_b32_e32 v110, v47
	v_mov_b32_e32 v120, v48
	v_mov_b32_e32 v121, v112
	v_mov_b32_e32 v112, v49
	v_mfma_f32_16x16x32_bf16 v[46:49], v[42:45], v[22:25], 0
	s_nop 7
	v_mov_b32_e32 v122, v46
	v_mov_b32_e32 v114, v47
	v_mov_b32_e32 v46, v48
	v_mov_b32_e32 v47, v116
	ds_write2_b64 v108, v[118:119], v[122:123] offset1:16
	ds_write2_b64 v108, v[120:121], v[46:47] offset0:128 offset1:144
	v_mov_b32_e32 v116, v49
	v_mfma_f32_16x16x32_bf16 v[46:49], v[42:45], v[18:21], 0
	v_mfma_f32_16x16x32_bf16 v[118:121], v[42:45], v[14:17], 0
	s_nop 6
	v_mov_b32_e32 v122, v46
	v_mov_b32_e32 v123, v118
	v_mov_b32_e32 v118, v47
	v_mov_b32_e32 v46, v48
	v_mov_b32_e32 v47, v120
	ds_write2_b64 v108, v[46:47], v[112:113] offset0:160 offset1:192
	v_mov_b32_e32 v120, v49
	v_mfma_f32_16x16x32_bf16 v[46:49], v[42:45], v[10:13], 0
	ds_write2_b64 v108, v[122:123], v[110:111] offset0:32 offset1:64
	ds_write2_b64 v108, v[114:115], v[118:119] offset0:80 offset1:96
	ds_write2_b64 v108, v[116:117], v[120:121] offset0:208 offset1:224
	v_mfma_f32_16x16x32_bf16 v[42:45], v[42:45], v[6:9], 0
	s_nop 3
	v_mov_b32_e32 v110, v46
	s_nop 2
	v_mov_b32_e32 v111, v42
	v_mov_b32_e32 v42, v47
	ds_write2st64_b64 v99, v[110:111], v[42:43] offset0:8 offset1:9
	v_mov_b32_e32 v42, v48
	v_mov_b32_e32 v43, v44
	v_mov_b32_e32 v44, v49
	ds_write2st64_b64 v99, v[42:43], v[44:45] offset0:10 offset1:11
	s_waitcnt lgkmcnt(0)
	s_nop 0
	ds_read_b64 v[140:141], v90 offset:4096
	ds_read_b64 v[142:143], v90 offset:4608
	ds_read_b64 v[144:145], v90 offset:5120
	ds_read_b64 v[146:147], v90 offset:5632
	ds_read_b64 v[148:149], v90 offset:6144
	ds_read_b64 v[150:151], v90 offset:6656
	ds_read_b64 v[152:153], v90 offset:7168
	ds_read_b64 v[154:155], v90 offset:7680
	v_xor_b32_e32 v44, 0x80000000, v53
	v_mov_b32_e32 v45, v52
	v_pk_mul_f32 v[44:45], v[0:1], v[44:45] op_sel_hi:[0,1]
	v_pk_fma_f32 v[44:45], v[84:85], v[52:53], v[44:45] op_sel_hi:[0,1,1]
	s_waitcnt lgkmcnt(7)
	v_pk_add_f32 v[42:43], v[44:45], v[140:141]
	ds_write2st64_b32 v98, v42, v43 offset1:1
	v_xor_b32_e32 v46, 0x80000000, v43
	v_mov_b32_e32 v47, v42
	v_pk_mul_f32 v[46:47], v[0:1], v[46:47] op_sel_hi:[0,1]
	v_pk_fma_f32 v[42:43], v[84:85], v[42:43], v[46:47] op_sel_hi:[0,1,1]
	s_waitcnt lgkmcnt(7)
	v_pk_add_f32 v[42:43], v[142:143], v[42:43]
	ds_write2_b32 v98, v42, v43 offset0:132 offset1:196
	v_xor_b32_e32 v46, 0x80000000, v43
	v_mov_b32_e32 v47, v42
	v_pk_mul_f32 v[46:47], v[0:1], v[46:47] op_sel_hi:[0,1]
	v_pk_fma_f32 v[42:43], v[84:85], v[42:43], v[46:47] op_sel_hi:[0,1,1]
	s_waitcnt lgkmcnt(7)
	v_pk_add_f32 v[42:43], v[144:145], v[42:43]
	ds_write2st64_b32 v78, v42, v43 offset0:4 offset1:5
	v_xor_b32_e32 v46, 0x80000000, v43
	v_mov_b32_e32 v47, v42
	v_pk_mul_f32 v[46:47], v[0:1], v[46:47] op_sel_hi:[0,1]
	v_pk_fma_f32 v[42:43], v[84:85], v[42:43], v[46:47] op_sel_hi:[0,1,1]
	s_waitcnt lgkmcnt(7)
	v_pk_add_f32 v[42:43], v[146:147], v[42:43]
	ds_write2st64_b32 v79, v42, v43 offset0:6 offset1:7
	v_xor_b32_e32 v46, 0x80000000, v43
	v_mov_b32_e32 v47, v42
	v_pk_mul_f32 v[46:47], v[0:1], v[46:47] op_sel_hi:[0,1]
	v_pk_fma_f32 v[42:43], v[84:85], v[42:43], v[46:47] op_sel_hi:[0,1,1]
	s_waitcnt lgkmcnt(7)
	v_pk_add_f32 v[42:43], v[148:149], v[42:43]
	ds_write2st64_b32 v80, v42, v43 offset0:8 offset1:9
	v_xor_b32_e32 v46, 0x80000000, v43
	v_mov_b32_e32 v47, v42
	v_pk_mul_f32 v[46:47], v[0:1], v[46:47] op_sel_hi:[0,1]
	v_pk_fma_f32 v[42:43], v[84:85], v[42:43], v[46:47] op_sel_hi:[0,1,1]
	s_waitcnt lgkmcnt(7)
	v_pk_add_f32 v[42:43], v[150:151], v[42:43]
	ds_write2st64_b32 v81, v42, v43 offset0:10 offset1:11
	v_xor_b32_e32 v46, 0x80000000, v43
	v_mov_b32_e32 v47, v42
	v_pk_mul_f32 v[46:47], v[0:1], v[46:47] op_sel_hi:[0,1]
	v_pk_fma_f32 v[42:43], v[84:85], v[42:43], v[46:47] op_sel_hi:[0,1,1]
	s_waitcnt lgkmcnt(7)
	v_pk_add_f32 v[42:43], v[152:153], v[42:43]
	ds_write2st64_b32 v86, v42, v43 offset0:12 offset1:13
	v_xor_b32_e32 v46, 0x80000000, v43
	v_mov_b32_e32 v47, v42
	v_pk_mul_f32 v[46:47], v[0:1], v[46:47] op_sel_hi:[0,1]
	v_pk_fma_f32 v[42:43], v[84:85], v[42:43], v[46:47] op_sel_hi:[0,1,1]
	s_waitcnt lgkmcnt(7)
	v_pk_add_f32 v[42:43], v[154:155], v[42:43]
	ds_write2st64_b32 v87, v42, v43 offset0:14 offset1:15
	ds_read_b64 v[140:141], v90 offset:8192
	ds_read_b64 v[142:143], v90 offset:8704
	ds_read_b64 v[144:145], v90 offset:9216
	ds_read_b64 v[146:147], v90 offset:9728
	ds_read_b64 v[148:149], v90 offset:10240
	ds_read_b64 v[150:151], v90 offset:10752
	ds_read_b64 v[152:153], v90 offset:11264
	ds_read_b64 v[154:155], v90 offset:11776
	v_xor_b32_e32 v46, 0x80000000, v43
	v_mov_b32_e32 v47, v42
	v_pk_mul_f32 v[46:47], v[0:1], v[46:47] op_sel_hi:[0,1]
	v_pk_fma_f32 v[42:43], v[84:85], v[42:43], v[46:47] op_sel_hi:[0,1,1]
	s_waitcnt lgkmcnt(7)
; __device__ __forceinline__ void s5_pass2_item(PP p, unsigned char* shm, int item, int l) {
;     ...
;         __syncthreads();
; #pragma unroll
;         for (int t = 0; t < 16; ++t) { s5_rec(q, *(const f32x2*)(buL + (t * 64 + lane) * 2), x); xs[t * 132 + lane] = x.x; xs[t * 132 + 64 + lane] = x.y; }
;         __syncthreads();
;         f32x4 y0 = (f32x4){0.f, 0.f, 0.f, 0.f}, y1 = y0;
;         const f32x4* xrow = (const f32x4*)(xs + cc * 132 + quad * 32);
; #pragma unroll
;         for (int i = 0; i < 8; ++i) { const f32x4 xv = xrow[i];
;             y0 = __builtin_amdgcn_mfma_f32_16x16x4f32(xv[0], cmr[4 * i + 0], y0, 0, 0, 0);
;             y1 = __builtin_amdgcn_mfma_f32_16x16x4f32(xv[1], cmr[4 * i + 1], y1, 0, 0, 0);
;             y0 = __builtin_amdgcn_mfma_f32_16x16x4f32(xv[2], cmr[4 * i + 2], y0, 0, 0, 0);
;             y1 = __builtin_amdgcn_mfma_f32_16x16x4f32(xv[3], cmr[4 * i + 3], y1, 0, 0, 0); }
	v_pk_add_f32 v[42:43], v[140:141], v[42:43]
	ds_write2st64_b32 v100, v42, v43 offset0:16 offset1:17
	v_xor_b32_e32 v46, 0x80000000, v43
	v_mov_b32_e32 v47, v42
	v_pk_mul_f32 v[46:47], v[0:1], v[46:47] op_sel_hi:[0,1]
	v_pk_fma_f32 v[42:43], v[84:85], v[42:43], v[46:47] op_sel_hi:[0,1,1]
	s_waitcnt lgkmcnt(7)
	v_pk_add_f32 v[42:43], v[142:143], v[42:43]
	ds_write2st64_b32 v101, v42, v43 offset0:18 offset1:19
	v_xor_b32_e32 v46, 0x80000000, v43
	v_mov_b32_e32 v47, v42
	v_pk_mul_f32 v[46:47], v[0:1], v[46:47] op_sel_hi:[0,1]
	v_pk_fma_f32 v[42:43], v[84:85], v[42:43], v[46:47] op_sel_hi:[0,1,1]
	s_waitcnt lgkmcnt(7)
	v_pk_add_f32 v[42:43], v[144:145], v[42:43]
	ds_write2st64_b32 v102, v42, v43 offset0:20 offset1:21
	v_xor_b32_e32 v46, 0x80000000, v43
	v_mov_b32_e32 v47, v42
	v_pk_mul_f32 v[46:47], v[0:1], v[46:47] op_sel_hi:[0,1]
	v_pk_fma_f32 v[42:43], v[84:85], v[42:43], v[46:47] op_sel_hi:[0,1,1]
	s_waitcnt lgkmcnt(7)
	v_pk_add_f32 v[42:43], v[146:147], v[42:43]
	ds_write2st64_b32 v103, v42, v43 offset0:22 offset1:23
	v_xor_b32_e32 v46, 0x80000000, v43
	v_mov_b32_e32 v47, v42
	v_pk_mul_f32 v[46:47], v[0:1], v[46:47] op_sel_hi:[0,1]
	v_pk_fma_f32 v[42:43], v[84:85], v[42:43], v[46:47] op_sel_hi:[0,1,1]
	s_waitcnt lgkmcnt(7)
	v_pk_add_f32 v[42:43], v[148:149], v[42:43]
	ds_write2st64_b32 v104, v42, v43 offset0:24 offset1:25
	v_xor_b32_e32 v46, 0x80000000, v43
	v_mov_b32_e32 v47, v42
	v_pk_mul_f32 v[46:47], v[0:1], v[46:47] op_sel_hi:[0,1]
	v_pk_fma_f32 v[42:43], v[84:85], v[42:43], v[46:47] op_sel_hi:[0,1,1]
	s_waitcnt lgkmcnt(7)
	v_pk_add_f32 v[42:43], v[150:151], v[42:43]
	ds_write2st64_b32 v105, v42, v43 offset0:26 offset1:27
	v_xor_b32_e32 v46, 0x80000000, v43
	v_mov_b32_e32 v47, v42
	v_pk_mul_f32 v[46:47], v[0:1], v[46:47] op_sel_hi:[0,1]
	v_pk_fma_f32 v[42:43], v[84:85], v[42:43], v[46:47] op_sel_hi:[0,1,1]
	s_waitcnt lgkmcnt(7)
	v_pk_add_f32 v[42:43], v[152:153], v[42:43]
	ds_write2st64_b32 v106, v42, v43 offset0:28 offset1:29
	v_xor_b32_e32 v46, 0x80000000, v43
	v_mov_b32_e32 v47, v42
	v_pk_mul_f32 v[46:47], v[0:1], v[46:47] op_sel_hi:[0,1]
	v_pk_fma_f32 v[42:43], v[84:85], v[42:43], v[46:47] op_sel_hi:[0,1,1]
	s_waitcnt lgkmcnt(7)
	v_pk_add_f32 v[46:47], v[154:155], v[42:43]
	ds_write2st64_b32 v107, v46, v47 offset0:30 offset1:31
	s_waitcnt lgkmcnt(0)
	s_nop 0
	v_or_b32_e32 v216, 16, v82
	v_mov_b32_e32 v217, v83
	v_lshlrev_b64 v[216:217], 9, v[216:217]
	v_lshl_add_u64 v[216:217], v[216:217], 0, v[50:51]
	v_lshlrev_b64 v[216:217], 1, v[216:217]
	v_lshl_add_u64 v[216:217], s[8:9], 0, v[216:217]
	global_load_ushort v204, v[216:217], off
	global_load_ushort v205, v[216:217], off offset:1024
	global_load_ushort v206, v[216:217], off offset:2048
	global_load_ushort v207, v[216:217], off offset:3072
	ds_read_b128 v[42:45], v89
	ds_read_b128 v[110:113], v89 offset:16
	ds_read_b128 v[114:117], v89 offset:32
	ds_read_b128 v[118:121], v89 offset:48
	s_waitcnt lgkmcnt(3)
	v_mfma_f32_16x16x4_f32 v[122:125], v42, v97, 0
	v_or_b32_e32 v48, 16, v82
	v_mov_b32_e32 v49, v83
	v_lshlrev_b64 v[48:49], 9, v[48:49]
	v_lshl_add_u64 v[48:49], v[48:49], 0, v[50:51]
	v_lshlrev_b64 v[48:49], 1, v[48:49]
	v_lshl_add_u64 v[52:53], s[8:9], 0, v[48:49]
	v_mfma_f32_16x16x4_f32 v[126:129], v43, v96, 0
	v_lshl_add_u64 v[48:49], s[28:29], 0, v[48:49]
	s_waitcnt vmcnt(3)
	v_lshlrev_b32_e32 v52, 16, v204
	v_mfma_f32_16x16x4_f32 v[122:125], v44, v95, v[122:125]
	v_mfma_f32_16x16x4_f32 v[42:45], v45, v94, v[126:129]
	s_waitcnt lgkmcnt(2)
	v_mfma_f32_16x16x4_f32 v[122:125], v110, v93, v[122:125]
	v_mfma_f32_16x16x4_f32 v[42:45], v111, v92, v[42:45]
	v_mfma_f32_16x16x4_f32 v[122:125], v112, v91, v[122:125]
	v_mfma_f32_16x16x4_f32 v[42:45], v113, v88, v[42:45]
	s_waitcnt lgkmcnt(1)
	v_mfma_f32_16x16x4_f32 v[110:113], v114, v85, v[122:125]
	v_mfma_f32_16x16x4_f32 v[42:45], v115, v55, v[42:45]
	v_mfma_f32_16x16x4_f32 v[110:113], v116, v56, v[110:113]
	v_mfma_f32_16x16x4_f32 v[42:45], v117, v57, v[42:45]
	ds_read_b128 v[114:117], v89 offset:64
	s_waitcnt lgkmcnt(1)
	v_mfma_f32_16x16x4_f32 v[110:113], v118, v58, v[110:113]
	v_mfma_f32_16x16x4_f32 v[42:45], v119, v59, v[42:45]
	v_mfma_f32_16x16x4_f32 v[110:113], v120, v60, v[110:113]
	v_mfma_f32_16x16x4_f32 v[42:45], v121, v61, v[42:45]
	s_waitcnt lgkmcnt(0)
	v_mfma_f32_16x16x4_f32 v[110:113], v114, v62, v[110:113]
	v_mfma_f32_16x16x4_f32 v[42:45], v115, v63, v[42:45]
	v_mfma_f32_16x16x4_f32 v[110:113], v116, v64, v[110:113]
	v_mfma_f32_16x16x4_f32 v[42:45], v117, v65, v[42:45]
	ds_read_b128 v[114:117], v89 offset:80
	s_waitcnt lgkmcnt(0)
	v_mfma_f32_16x16x4_f32 v[110:113], v114, v66, v[110:113]
	v_mfma_f32_16x16x4_f32 v[42:45], v115, v67, v[42:45]
	v_mfma_f32_16x16x4_f32 v[110:113], v116, v68, v[110:113]
	v_mfma_f32_16x16x4_f32 v[42:45], v117, v69, v[42:45]
	ds_read_b128 v[114:117], v89 offset:96
	s_waitcnt lgkmcnt(0)
	v_mfma_f32_16x16x4_f32 v[110:113], v114, v70, v[110:113]
	v_mfma_f32_16x16x4_f32 v[42:45], v115, v71, v[42:45]
	v_mfma_f32_16x16x4_f32 v[110:113], v116, v72, v[110:113]
	v_mfma_f32_16x16x4_f32 v[42:45], v117, v73, v[42:45]
	ds_read_b128 v[114:117], v89 offset:112
	s_waitcnt lgkmcnt(0)
; __device__ __forceinline__ float bf2f(bf16_t v) { return __uint_as_float(((unsigned)v) << 16); }
; __device__ __forceinline__ bf16_t f2bf(float f) { unsigned u = __float_as_uint(f); u += 0x7FFFu + ((u >> 16) & 1u); return (bf16_t)(u >> 16); }
; __device__ __forceinline__ void s5_bu16(const S5Frag& f, const bf16x8 uf, float* buL, int lane) {
;     const int jj = lane & 15, quad = lane >> 4;
; #pragma unroll
;     for (int nt = 0; nt < 4; ++nt) {
;         const f32x4 z = (f32x4){0.f, 0.f, 0.f, 0.f};
;         const f32x4 dre = __builtin_amdgcn_mfma_f32_16x16x32_bf16(uf, f.bfr[nt], z, 0, 0, 0);
;         const f32x4 dim = __builtin_amdgcn_mfma_f32_16x16x32_bf16(uf, f.bfr[nt + 4], z, 0, 0, 0);
; #pragma unroll
;         for (int r = 0; r < 4; ++r) *(f32x2*)(buL + ((4 * quad + r) * 64 + 16 * nt + jj) * 2) = (f32x2){dre[r], dim[r]};
;     }
; }
; __device__ __forceinline__ void s5_pass2_item(PP p, unsigned char* shm, int item, int l) {
;     ...
;         f32x4 y0 = (f32x4){0.f, 0.f, 0.f, 0.f}, y1 = y0;
;         const f32x4* xrow = (const f32x4*)(xs + cc * 132 + quad * 32);
; #pragma unroll
;         for (int i = 0; i < 8; ++i) { const f32x4 xv = xrow[i];
;             y0 = __builtin_amdgcn_mfma_f32_16x16x4f32(xv[0], cmr[4 * i + 0], y0, 0, 0, 0);
;             y1 = __builtin_amdgcn_mfma_f32_16x16x4f32(xv[1], cmr[4 * i + 1], y1, 0, 0, 0);
;             y0 = __builtin_amdgcn_mfma_f32_16x16x4f32(xv[2], cmr[4 * i + 2], y0, 0, 0, 0);
;             y1 = __builtin_amdgcn_mfma_f32_16x16x4f32(xv[3], cmr[4 * i + 3], y1, 0, 0, 0); }
;         const f32x4 y = y0 + y1;
; #pragma unroll
;         for (int r = 0; r < 4; ++r) { const int tl = sc * 16 + quad * 4 + r;
;             const float v = y[r] + dsk * bf2f(proj[PJ_UA + (row0 + tl) * 512 + g * 16 + cc]);
;             const float z = 0.7978845608028654f * (v + 0.044715f * v * v * v);
;             const float th = 1.0f - 2.0f / (__expf(2.0f * z) + 1.0f);
;             Gout[(row0 + tl) * 512 + g * 16 + cc] = f2bf(0.5f * v * (1.0f + th)); }
	v_mfma_f32_16x16x4_f32 v[110:113], v114, v74, v[110:113]
	v_mfma_f32_16x16x4_f32 v[42:45], v115, v75, v[42:45]
	v_mfma_f32_16x16x4_f32 v[110:113], v116, v76, v[110:113]
	v_mfma_f32_16x16x4_f32 v[42:45], v117, v77, v[42:45]
	v_mfma_f32_16x16x32_bf16 v[114:117], v[38:41], v[30:33], 0
	s_nop 8
	v_add_f32_e64 v42, v110, v42
	v_add_f32_e64 v43, v111, v43
	v_pk_add_f32 v[44:45], v[112:113], v[44:45]
	v_fma_f32 v42, v54, v52, v42
	v_mul_f32_e32 v52, 0x3d372713, v42
	v_mul_f32_e32 v52, v42, v52
	v_fma_f32 v52, v42, v52, v42
	v_mul_f32_e32 v52, 0x3f4c422a, v52
	v_add_f32_e32 v52, v52, v52
	v_mul_f32_e32 v52, 0x3fb8aa3b, v52
	v_exp_f32_e32 v52, v52
	v_mul_f32_e32 v42, 0.5, v42
	v_mov_b32_e32 v119, v114
	v_mfma_f32_16x16x32_bf16 v[30:33], v[2:5], v[30:33], 0
	v_add_f32_e32 v52, 1.0, v52
	v_div_scale_f32 v53, s[2:3], v52, v52, 2.0
	v_rcp_f32_e32 v109, v53
	s_nop 0
	v_fma_f32 v110, -v53, v109, 1.0
	v_fmac_f32_e32 v109, v110, v109
	v_div_scale_f32 v110, vcc, 2.0, v52, 2.0
	v_mul_f32_e32 v111, v110, v109
	v_fma_f32 v112, -v53, v111, v110
	v_fmac_f32_e32 v111, v112, v109
	v_fma_f32 v53, -v53, v111, v110
	v_div_fmas_f32 v53, v53, v109, v111
	v_div_fixup_f32 v52, v53, v52, 2.0
	v_sub_f32_e32 v52, 1.0, v52
	v_add_f32_e32 v52, 1.0, v52
	v_mul_f32_e32 v42, v42, v52
	v_bfe_u32 v52, v42, 16, 1
	v_add3_u32 v42, v42, v52, s31
	global_store_short_d16_hi v[48:49], v42, off
	v_or_b32_e32 v48, 17, v82
	v_mov_b32_e32 v49, v83
	v_lshlrev_b64 v[48:49], 9, v[48:49]
	v_lshl_add_u64 v[48:49], v[48:49], 0, v[50:51]
	v_lshlrev_b64 v[48:49], 1, v[48:49]
	v_lshl_add_u64 v[52:53], s[8:9], 0, v[48:49]
	s_waitcnt vmcnt(3)
	v_lshlrev_b32_e32 v42, 16, v205
	v_fmac_f32_e32 v43, v54, v42
	v_mul_f32_e32 v42, 0x3d372713, v43
	v_mul_f32_e32 v42, v43, v42
	v_fma_f32 v42, v43, v42, v43
	v_mul_f32_e32 v42, 0x3f4c422a, v42
	v_add_f32_e32 v42, v42, v42
	v_mul_f32_e32 v42, 0x3fb8aa3b, v42
	v_exp_f32_e32 v42, v42
	v_mul_f32_e32 v43, 0.5, v43
	v_add_f32_e32 v42, 1.0, v42
	v_div_scale_f32 v52, s[2:3], v42, v42, 2.0
	v_rcp_f32_e32 v53, v52
	s_nop 0
	v_fma_f32 v109, -v52, v53, 1.0
	v_fmac_f32_e32 v53, v109, v53
	v_div_scale_f32 v109, vcc, 2.0, v42, 2.0
	v_mul_f32_e32 v110, v109, v53
	v_fma_f32 v111, -v52, v110, v109
	v_fmac_f32_e32 v110, v111, v53
	v_fma_f32 v52, -v52, v110, v109
	v_div_fmas_f32 v52, v52, v53, v110
	v_div_fixup_f32 v42, v52, v42, 2.0
	v_sub_f32_e32 v42, 1.0, v42
	v_add_f32_e32 v42, 1.0, v42
	v_mul_f32_e32 v42, v43, v42
	v_bfe_u32 v43, v42, 16, 1
	v_add3_u32 v52, v42, v43, s31
	v_lshl_add_u64 v[42:43], s[28:29], 0, v[48:49]
	global_store_short_d16_hi v[42:43], v52, off
	v_or_b32_e32 v42, 18, v82
	v_mov_b32_e32 v43, v83
	v_lshlrev_b64 v[42:43], 9, v[42:43]
	v_lshl_add_u64 v[42:43], v[42:43], 0, v[50:51]
	v_lshlrev_b64 v[42:43], 1, v[42:43]
	v_lshl_add_u64 v[48:49], s[8:9], 0, v[42:43]
	v_lshl_add_u64 v[42:43], s[28:29], 0, v[42:43]
	s_waitcnt vmcnt(3)
	v_lshlrev_b32_e32 v48, 16, v206
	v_fma_f32 v44, v54, v48, v44
	v_mul_f32_e32 v48, 0x3d372713, v44
	v_mul_f32_e32 v48, v44, v48
	v_fma_f32 v48, v44, v48, v44
	v_mul_f32_e32 v48, 0x3f4c422a, v48
	v_add_f32_e32 v48, v48, v48
	v_mul_f32_e32 v48, 0x3fb8aa3b, v48
	v_exp_f32_e32 v48, v48
	v_mul_f32_e32 v44, 0.5, v44
	v_add_f32_e32 v48, 1.0, v48
	v_div_scale_f32 v49, s[2:3], v48, v48, 2.0
	v_rcp_f32_e32 v52, v49
	s_nop 0
	v_fma_f32 v53, -v49, v52, 1.0
	v_fmac_f32_e32 v52, v53, v52
	v_div_scale_f32 v53, vcc, 2.0, v48, 2.0
	v_mul_f32_e32 v109, v53, v52
	v_fma_f32 v110, -v49, v109, v53
	v_fmac_f32_e32 v109, v110, v52
	v_fma_f32 v49, -v49, v109, v53
	v_div_fmas_f32 v49, v49, v52, v109
	v_div_fixup_f32 v48, v49, v48, 2.0
	v_sub_f32_e32 v48, 1.0, v48
	v_add_f32_e32 v48, 1.0, v48
	v_mul_f32_e32 v44, v44, v48
	v_bfe_u32 v48, v44, 16, 1
	v_add3_u32 v44, v44, v48, s31
	global_store_short_d16_hi v[42:43], v44, off
	v_or_b32_e32 v42, 19, v82
	v_mov_b32_e32 v43, v83
	v_lshlrev_b64 v[42:43], 9, v[42:43]
	v_lshl_add_u64 v[42:43], v[42:43], 0, v[50:51]
	v_lshlrev_b64 v[42:43], 1, v[42:43]
	v_lshl_add_u64 v[48:49], s[8:9], 0, v[42:43]
	v_lshl_add_u64 v[42:43], s[28:29], 0, v[42:43]
	v_mfma_f32_16x16x32_bf16 v[110:113], v[38:41], v[26:29], 0
	s_waitcnt vmcnt(3)
	v_lshlrev_b32_e32 v44, 16, v207
	v_fmac_f32_e32 v45, v54, v44
	v_mul_f32_e32 v44, 0x3d372713, v45
	v_mul_f32_e32 v44, v45, v44
	v_fma_f32 v44, v45, v44, v45
	v_mul_f32_e32 v44, 0x3f4c422a, v44
	v_add_f32_e32 v44, v44, v44
	v_mul_f32_e32 v44, 0x3fb8aa3b, v44
	v_exp_f32_e32 v44, v44
	v_mul_f32_e32 v45, 0.5, v45
	v_add_f32_e32 v44, 1.0, v44
	v_div_scale_f32 v48, s[2:3], v44, v44, 2.0
	v_rcp_f32_e32 v49, v48
	s_nop 0
	v_fma_f32 v52, -v48, v49, 1.0
	v_fmac_f32_e32 v49, v52, v49
	v_div_scale_f32 v52, vcc, 2.0, v44, 2.0
	v_mul_f32_e32 v53, v52, v49
	v_fma_f32 v109, -v48, v53, v52
	v_fmac_f32_e32 v53, v109, v49
	v_fma_f32 v48, -v48, v53, v52
	v_div_fmas_f32 v48, v48, v49, v53
	v_div_fixup_f32 v44, v48, v44, 2.0
	v_sub_f32_e32 v44, 1.0, v44
	v_add_f32_e32 v44, 1.0, v44
	v_mul_f32_e32 v44, v45, v44
	v_bfe_u32 v45, v44, 16, 1
	v_add3_u32 v44, v44, v45, s31
	global_store_short_d16_hi v[42:43], v44, off
	v_mfma_f32_16x16x32_bf16 v[42:45], v[38:41], v[34:37], 0
	v_mov_b32_e32 v48, v110
	v_mov_b32_e32 v52, v112
	s_nop 0
	s_nop 4
	v_mov_b32_e32 v49, v42
	v_mov_b32_e32 v42, v111
	v_mov_b32_e32 v53, v44
	v_mov_b32_e32 v44, v113
	v_mfma_f32_16x16x32_bf16 v[110:113], v[38:41], v[22:25], 0
	v_mfma_f32_16x16x32_bf16 v[22:25], v[2:5], v[22:25], 0
	s_nop 6
	v_mov_b32_e32 v118, v110
	ds_write2_b64 v108, v[48:49], v[118:119] offset1:16
	v_mov_b32_e32 v114, v111
	v_mov_b32_e32 v48, v112
	v_mov_b32_e32 v49, v116
	v_mov_b32_e32 v116, v113
	v_mfma_f32_16x16x32_bf16 v[110:113], v[38:41], v[18:21], 0
	ds_write2_b64 v108, v[52:53], v[48:49] offset0:128 offset1:144
	v_mfma_f32_16x16x32_bf16 v[118:121], v[38:41], v[14:17], 0
	v_mfma_f32_16x16x32_bf16 v[18:21], v[2:5], v[18:21], 0
	s_nop 4
	v_mov_b32_e32 v48, v110
	s_nop 0
	v_mov_b32_e32 v49, v118
	ds_write2_b64 v108, v[48:49], v[42:43] offset0:32 offset1:64
	v_mov_b32_e32 v42, v112
	v_mov_b32_e32 v43, v120
	ds_write2_b64 v108, v[42:43], v[44:45] offset0:160 offset1:192
	v_mfma_f32_16x16x32_bf16 v[42:45], v[38:41], v[10:13], 0
	v_mov_b32_e32 v118, v111
	v_mov_b32_e32 v120, v113
	ds_write2_b64 v108, v[114:115], v[118:119] offset0:80 offset1:96
	v_mfma_f32_16x16x32_bf16 v[38:41], v[38:41], v[6:9], 0
	ds_write2_b64 v108, v[116:117], v[120:121] offset0:208 offset1:224
	s_nop 2
	v_mov_b32_e32 v48, v42
	v_mfma_f32_16x16x32_bf16 v[14:17], v[2:5], v[14:17], 0
	v_mfma_f32_16x16x32_bf16 v[10:13], v[2:5], v[10:13], 0
	s_nop 0
	v_mov_b32_e32 v49, v38
	v_mov_b32_e32 v38, v43
	ds_write2st64_b64 v99, v[48:49], v[38:39] offset0:8 offset1:9
	v_mov_b32_e32 v38, v44
	v_mov_b32_e32 v39, v40
	v_mov_b32_e32 v40, v45
	ds_write2st64_b64 v99, v[38:39], v[40:41] offset0:10 offset1:11
	s_waitcnt lgkmcnt(0)
; __device__ __forceinline__ void s5_pass2_item(PP p, unsigned char* shm, int item, int l) {
;     ...
;         s5_bu16(f, uf[sc], buL, lane);
;         __syncthreads();
; #pragma unroll
;         for (int t = 0; t < 16; ++t) { s5_rec(q, *(const f32x2*)(buL + (t * 64 + lane) * 2), x); xs[t * 132 + lane] = x.x; xs[t * 132 + 64 + lane] = x.y; }
;         __syncthreads();
	s_nop 0
	ds_read_b64 v[140:141], v90 offset:4096
	ds_read_b64 v[142:143], v90 offset:4608
	ds_read_b64 v[144:145], v90 offset:5120
	ds_read_b64 v[146:147], v90 offset:5632
	ds_read_b64 v[148:149], v90 offset:6144
	ds_read_b64 v[150:151], v90 offset:6656
	ds_read_b64 v[152:153], v90 offset:7168
	ds_read_b64 v[154:155], v90 offset:7680
	v_xor_b32_e32 v40, 0x80000000, v47
	v_mov_b32_e32 v41, v46
	v_pk_mul_f32 v[40:41], v[0:1], v[40:41] op_sel_hi:[0,1]
	v_pk_fma_f32 v[40:41], v[84:85], v[46:47], v[40:41] op_sel_hi:[0,1,1]
	s_waitcnt lgkmcnt(7)
	v_pk_add_f32 v[38:39], v[40:41], v[140:141]
	ds_write2st64_b32 v98, v38, v39 offset1:1
	v_xor_b32_e32 v42, 0x80000000, v39
	v_mov_b32_e32 v43, v38
	v_pk_mul_f32 v[42:43], v[0:1], v[42:43] op_sel_hi:[0,1]
	v_pk_fma_f32 v[38:39], v[84:85], v[38:39], v[42:43] op_sel_hi:[0,1,1]
	s_waitcnt lgkmcnt(7)
	v_pk_add_f32 v[38:39], v[142:143], v[38:39]
	ds_write2_b32 v98, v38, v39 offset0:132 offset1:196
	v_xor_b32_e32 v42, 0x80000000, v39
	v_mov_b32_e32 v43, v38
	v_pk_mul_f32 v[42:43], v[0:1], v[42:43] op_sel_hi:[0,1]
	v_pk_fma_f32 v[38:39], v[84:85], v[38:39], v[42:43] op_sel_hi:[0,1,1]
	s_waitcnt lgkmcnt(7)
	v_pk_add_f32 v[38:39], v[144:145], v[38:39]
	ds_write2st64_b32 v78, v38, v39 offset0:4 offset1:5
	v_xor_b32_e32 v42, 0x80000000, v39
	v_mov_b32_e32 v43, v38
	v_pk_mul_f32 v[42:43], v[0:1], v[42:43] op_sel_hi:[0,1]
	v_pk_fma_f32 v[38:39], v[84:85], v[38:39], v[42:43] op_sel_hi:[0,1,1]
	s_waitcnt lgkmcnt(7)
	v_pk_add_f32 v[38:39], v[146:147], v[38:39]
	ds_write2st64_b32 v79, v38, v39 offset0:6 offset1:7
	v_xor_b32_e32 v42, 0x80000000, v39
	v_mov_b32_e32 v43, v38
	v_pk_mul_f32 v[42:43], v[0:1], v[42:43] op_sel_hi:[0,1]
	v_pk_fma_f32 v[38:39], v[84:85], v[38:39], v[42:43] op_sel_hi:[0,1,1]
	s_waitcnt lgkmcnt(7)
	v_pk_add_f32 v[38:39], v[148:149], v[38:39]
	ds_write2st64_b32 v80, v38, v39 offset0:8 offset1:9
	v_xor_b32_e32 v42, 0x80000000, v39
	v_mov_b32_e32 v43, v38
	v_pk_mul_f32 v[42:43], v[0:1], v[42:43] op_sel_hi:[0,1]
	v_pk_fma_f32 v[38:39], v[84:85], v[38:39], v[42:43] op_sel_hi:[0,1,1]
	s_waitcnt lgkmcnt(7)
	v_pk_add_f32 v[38:39], v[150:151], v[38:39]
	ds_write2st64_b32 v81, v38, v39 offset0:10 offset1:11
	v_xor_b32_e32 v42, 0x80000000, v39
	v_mov_b32_e32 v43, v38
	v_pk_mul_f32 v[42:43], v[0:1], v[42:43] op_sel_hi:[0,1]
	v_pk_fma_f32 v[38:39], v[84:85], v[38:39], v[42:43] op_sel_hi:[0,1,1]
	s_waitcnt lgkmcnt(7)
	v_pk_add_f32 v[38:39], v[152:153], v[38:39]
	ds_write2st64_b32 v86, v38, v39 offset0:12 offset1:13
	v_xor_b32_e32 v42, 0x80000000, v39
	v_mov_b32_e32 v43, v38
	v_pk_mul_f32 v[42:43], v[0:1], v[42:43] op_sel_hi:[0,1]
	v_pk_fma_f32 v[38:39], v[84:85], v[38:39], v[42:43] op_sel_hi:[0,1,1]
	s_waitcnt lgkmcnt(7)
	v_pk_add_f32 v[38:39], v[154:155], v[38:39]
	ds_write2st64_b32 v87, v38, v39 offset0:14 offset1:15
	ds_read_b64 v[140:141], v90 offset:8192
	ds_read_b64 v[142:143], v90 offset:8704
	ds_read_b64 v[144:145], v90 offset:9216
	ds_read_b64 v[146:147], v90 offset:9728
	ds_read_b64 v[148:149], v90 offset:10240
	ds_read_b64 v[150:151], v90 offset:10752
	ds_read_b64 v[152:153], v90 offset:11264
	ds_read_b64 v[154:155], v90 offset:11776
	v_xor_b32_e32 v42, 0x80000000, v39
	v_mov_b32_e32 v43, v38
	v_pk_mul_f32 v[42:43], v[0:1], v[42:43] op_sel_hi:[0,1]
	v_pk_fma_f32 v[38:39], v[84:85], v[38:39], v[42:43] op_sel_hi:[0,1,1]
	s_waitcnt lgkmcnt(7)
	v_pk_add_f32 v[38:39], v[140:141], v[38:39]
	ds_write2st64_b32 v100, v38, v39 offset0:16 offset1:17
	v_xor_b32_e32 v42, 0x80000000, v39
	v_mov_b32_e32 v43, v38
	v_pk_mul_f32 v[42:43], v[0:1], v[42:43] op_sel_hi:[0,1]
	v_pk_fma_f32 v[38:39], v[84:85], v[38:39], v[42:43] op_sel_hi:[0,1,1]
	s_waitcnt lgkmcnt(7)
	v_pk_add_f32 v[38:39], v[142:143], v[38:39]
	ds_write2st64_b32 v101, v38, v39 offset0:18 offset1:19
	v_xor_b32_e32 v42, 0x80000000, v39
	v_mov_b32_e32 v43, v38
	v_pk_mul_f32 v[42:43], v[0:1], v[42:43] op_sel_hi:[0,1]
	v_pk_fma_f32 v[38:39], v[84:85], v[38:39], v[42:43] op_sel_hi:[0,1,1]
	s_waitcnt lgkmcnt(7)
	v_pk_add_f32 v[38:39], v[144:145], v[38:39]
	ds_write2st64_b32 v102, v38, v39 offset0:20 offset1:21
	v_xor_b32_e32 v42, 0x80000000, v39
	v_mov_b32_e32 v43, v38
	v_pk_mul_f32 v[42:43], v[0:1], v[42:43] op_sel_hi:[0,1]
	v_pk_fma_f32 v[38:39], v[84:85], v[38:39], v[42:43] op_sel_hi:[0,1,1]
	s_waitcnt lgkmcnt(7)
	v_pk_add_f32 v[38:39], v[146:147], v[38:39]
	ds_write2st64_b32 v103, v38, v39 offset0:22 offset1:23
	v_xor_b32_e32 v42, 0x80000000, v39
	v_mov_b32_e32 v43, v38
	v_pk_mul_f32 v[42:43], v[0:1], v[42:43] op_sel_hi:[0,1]
	v_pk_fma_f32 v[38:39], v[84:85], v[38:39], v[42:43] op_sel_hi:[0,1,1]
	s_waitcnt lgkmcnt(7)
	v_pk_add_f32 v[38:39], v[148:149], v[38:39]
	ds_write2st64_b32 v104, v38, v39 offset0:24 offset1:25
	v_xor_b32_e32 v42, 0x80000000, v39
	v_mov_b32_e32 v43, v38
	v_pk_mul_f32 v[42:43], v[0:1], v[42:43] op_sel_hi:[0,1]
	v_pk_fma_f32 v[38:39], v[84:85], v[38:39], v[42:43] op_sel_hi:[0,1,1]
	s_waitcnt lgkmcnt(7)
	v_pk_add_f32 v[38:39], v[150:151], v[38:39]
	ds_write2st64_b32 v105, v38, v39 offset0:26 offset1:27
	v_xor_b32_e32 v42, 0x80000000, v39
	v_mov_b32_e32 v43, v38
	v_pk_mul_f32 v[42:43], v[0:1], v[42:43] op_sel_hi:[0,1]
	v_pk_fma_f32 v[38:39], v[84:85], v[38:39], v[42:43] op_sel_hi:[0,1,1]
	s_waitcnt lgkmcnt(7)
	v_pk_add_f32 v[38:39], v[152:153], v[38:39]
	ds_write2st64_b32 v106, v38, v39 offset0:28 offset1:29
	v_xor_b32_e32 v42, 0x80000000, v39
	v_mov_b32_e32 v43, v38
	v_pk_mul_f32 v[42:43], v[0:1], v[42:43] op_sel_hi:[0,1]
	v_pk_fma_f32 v[38:39], v[84:85], v[38:39], v[42:43] op_sel_hi:[0,1,1]
	s_waitcnt lgkmcnt(7)
	v_pk_add_f32 v[38:39], v[154:155], v[38:39]
	ds_write2st64_b32 v107, v38, v39 offset0:30 offset1:31
	s_waitcnt lgkmcnt(0)
; __device__ __forceinline__ float bf2f(bf16_t v) { return __uint_as_float(((unsigned)v) << 16); }
; __device__ __forceinline__ bf16_t f2bf(float f) { unsigned u = __float_as_uint(f); u += 0x7FFFu + ((u >> 16) & 1u); return (bf16_t)(u >> 16); }
; __device__ __forceinline__ void s5_pass2_item(PP p, unsigned char* shm, int item, int l) {
;     ...
;         f32x4 y0 = (f32x4){0.f, 0.f, 0.f, 0.f}, y1 = y0;
;         const f32x4* xrow = (const f32x4*)(xs + cc * 132 + quad * 32);
; #pragma unroll
;         for (int i = 0; i < 8; ++i) { const f32x4 xv = xrow[i];
;             y0 = __builtin_amdgcn_mfma_f32_16x16x4f32(xv[0], cmr[4 * i + 0], y0, 0, 0, 0);
;             y1 = __builtin_amdgcn_mfma_f32_16x16x4f32(xv[1], cmr[4 * i + 1], y1, 0, 0, 0);
;             y0 = __builtin_amdgcn_mfma_f32_16x16x4f32(xv[2], cmr[4 * i + 2], y0, 0, 0, 0);
;             y1 = __builtin_amdgcn_mfma_f32_16x16x4f32(xv[3], cmr[4 * i + 3], y1, 0, 0, 0); }
;         const f32x4 y = y0 + y1;
; #pragma unroll
;         for (int r = 0; r < 4; ++r) { const int tl = sc * 16 + quad * 4 + r;
;             const float v = y[r] + dsk * bf2f(proj[PJ_UA + (row0 + tl) * 512 + g * 16 + cc]);
;             const float z = 0.7978845608028654f * (v + 0.044715f * v * v * v);
;             const float th = 1.0f - 2.0f / (__expf(2.0f * z) + 1.0f);
;             Gout[(row0 + tl) * 512 + g * 16 + cc] = f2bf(0.5f * v * (1.0f + th)); }
	s_nop 0
	v_or_b32_e32 v216, 32, v82
	v_mov_b32_e32 v217, v83
	v_lshlrev_b64 v[216:217], 9, v[216:217]
	v_lshl_add_u64 v[216:217], v[216:217], 0, v[50:51]
	v_lshlrev_b64 v[216:217], 1, v[216:217]
	v_lshl_add_u64 v[216:217], s[8:9], 0, v[216:217]
	global_load_ushort v208, v[216:217], off
	global_load_ushort v209, v[216:217], off offset:1024
	global_load_ushort v210, v[216:217], off offset:2048
	global_load_ushort v211, v[216:217], off offset:3072
	ds_read_b128 v[40:43], v89
	ds_read_b128 v[44:47], v89 offset:16
	ds_read_b128 v[110:113], v89 offset:32
	ds_read_b128 v[114:117], v89 offset:48
	s_waitcnt lgkmcnt(3)
	v_mfma_f32_16x16x4_f32 v[118:121], v40, v97, 0
	v_mfma_f32_16x16x4_f32 v[122:125], v41, v96, 0
	v_mfma_f32_16x16x4_f32 v[118:121], v42, v95, v[118:121]
	v_mfma_f32_16x16x4_f32 v[40:43], v43, v94, v[122:125]
	s_waitcnt lgkmcnt(2)
	v_mfma_f32_16x16x4_f32 v[118:121], v44, v93, v[118:121]
	v_mfma_f32_16x16x4_f32 v[40:43], v45, v92, v[40:43]
	v_mfma_f32_16x16x4_f32 v[118:121], v46, v91, v[118:121]
	v_mfma_f32_16x16x4_f32 v[40:43], v47, v88, v[40:43]
	s_waitcnt lgkmcnt(1)
	v_mfma_f32_16x16x4_f32 v[44:47], v110, v85, v[118:121]
	v_mfma_f32_16x16x4_f32 v[40:43], v111, v55, v[40:43]
	v_mfma_f32_16x16x4_f32 v[44:47], v112, v56, v[44:47]
	v_mfma_f32_16x16x4_f32 v[40:43], v113, v57, v[40:43]
	ds_read_b128 v[110:113], v89 offset:64
	s_waitcnt lgkmcnt(1)
	v_mfma_f32_16x16x4_f32 v[44:47], v114, v58, v[44:47]
	v_mfma_f32_16x16x4_f32 v[40:43], v115, v59, v[40:43]
	v_mfma_f32_16x16x4_f32 v[44:47], v116, v60, v[44:47]
	v_mfma_f32_16x16x4_f32 v[40:43], v117, v61, v[40:43]
	s_waitcnt lgkmcnt(0)
	v_mfma_f32_16x16x4_f32 v[44:47], v110, v62, v[44:47]
	v_mfma_f32_16x16x4_f32 v[40:43], v111, v63, v[40:43]
	v_mfma_f32_16x16x4_f32 v[44:47], v112, v64, v[44:47]
	v_mfma_f32_16x16x4_f32 v[40:43], v113, v65, v[40:43]
	ds_read_b128 v[110:113], v89 offset:80
	s_waitcnt lgkmcnt(0)
	v_mfma_f32_16x16x4_f32 v[44:47], v110, v66, v[44:47]
	v_mfma_f32_16x16x4_f32 v[40:43], v111, v67, v[40:43]
	v_mfma_f32_16x16x4_f32 v[44:47], v112, v68, v[44:47]
	v_mfma_f32_16x16x4_f32 v[40:43], v113, v69, v[40:43]
	ds_read_b128 v[110:113], v89 offset:96
	s_waitcnt lgkmcnt(0)
	v_mfma_f32_16x16x4_f32 v[44:47], v110, v70, v[44:47]
	v_mfma_f32_16x16x4_f32 v[40:43], v111, v71, v[40:43]
	v_mfma_f32_16x16x4_f32 v[44:47], v112, v72, v[44:47]
	v_mfma_f32_16x16x4_f32 v[40:43], v113, v73, v[40:43]
	ds_read_b128 v[110:113], v89 offset:112
	s_waitcnt lgkmcnt(0)
	v_mfma_f32_16x16x4_f32 v[44:47], v110, v74, v[44:47]
	v_mfma_f32_16x16x4_f32 v[40:43], v111, v75, v[40:43]
	v_mfma_f32_16x16x4_f32 v[44:47], v112, v76, v[44:47]
	v_mfma_f32_16x16x4_f32 v[40:43], v113, v77, v[40:43]
	s_nop 9
	v_pk_add_f32 v[40:41], v[44:45], v[40:41]
	v_or_b32_e32 v44, 32, v82
	v_mov_b32_e32 v45, v83
	v_lshlrev_b64 v[44:45], 9, v[44:45]
	v_lshl_add_u64 v[44:45], v[44:45], 0, v[50:51]
	v_lshlrev_b64 v[44:45], 1, v[44:45]
	v_pk_add_f32 v[42:43], v[46:47], v[42:43]
	v_lshl_add_u64 v[46:47], s[8:9], 0, v[44:45]
	v_lshl_add_u64 v[44:45], s[28:29], 0, v[44:45]
	s_waitcnt vmcnt(3)
	v_lshlrev_b32_e32 v46, 16, v208
	v_fma_f32 v40, v54, v46, v40
	v_mul_f32_e32 v46, 0x3d372713, v40
	v_mul_f32_e32 v46, v40, v46
	v_fma_f32 v46, v40, v46, v40
	v_mul_f32_e32 v46, 0x3f4c422a, v46
	v_add_f32_e32 v46, v46, v46
	v_mul_f32_e32 v46, 0x3fb8aa3b, v46
	v_exp_f32_e32 v46, v46
	v_mul_f32_e32 v40, 0.5, v40
	v_add_f32_e32 v46, 1.0, v46
	v_div_scale_f32 v47, s[2:3], v46, v46, 2.0
	v_rcp_f32_e32 v48, v47
	s_nop 0
	v_fma_f32 v49, -v47, v48, 1.0
	v_fmac_f32_e32 v48, v49, v48
	v_div_scale_f32 v49, vcc, 2.0, v46, 2.0
	v_mul_f32_e32 v52, v49, v48
	v_fma_f32 v53, -v47, v52, v49
	v_fmac_f32_e32 v52, v53, v48
	v_fma_f32 v47, -v47, v52, v49
	v_div_fmas_f32 v47, v47, v48, v52
	v_div_fixup_f32 v46, v47, v46, 2.0
	v_sub_f32_e32 v46, 1.0, v46
	v_add_f32_e32 v46, 1.0, v46
	v_mul_f32_e32 v40, v40, v46
	v_bfe_u32 v46, v40, 16, 1
	v_add3_u32 v40, v40, v46, s31
	global_store_short_d16_hi v[44:45], v40, off
	v_or_b32_e32 v44, 33, v82
	v_mov_b32_e32 v45, v83
	v_lshlrev_b64 v[44:45], 9, v[44:45]
	v_lshl_add_u64 v[44:45], v[44:45], 0, v[50:51]
	v_lshlrev_b64 v[44:45], 1, v[44:45]
	v_lshl_add_u64 v[46:47], s[8:9], 0, v[44:45]
	s_waitcnt vmcnt(3)
	v_lshlrev_b32_e32 v40, 16, v209
	v_fmac_f32_e32 v41, v54, v40
	v_mul_f32_e32 v40, 0x3d372713, v41
	v_mul_f32_e32 v40, v41, v40
	v_fma_f32 v40, v41, v40, v41
	v_mul_f32_e32 v40, 0x3f4c422a, v40
	v_add_f32_e32 v40, v40, v40
	v_mul_f32_e32 v40, 0x3fb8aa3b, v40
	v_exp_f32_e32 v40, v40
	v_mul_f32_e32 v41, 0.5, v41
	v_add_f32_e32 v40, 1.0, v40
	v_div_scale_f32 v46, s[2:3], v40, v40, 2.0
	v_rcp_f32_e32 v47, v46
	s_nop 0
	v_fma_f32 v48, -v46, v47, 1.0
	v_fmac_f32_e32 v47, v48, v47
	v_div_scale_f32 v48, vcc, 2.0, v40, 2.0
	v_mul_f32_e32 v49, v48, v47
	v_fma_f32 v52, -v46, v49, v48
	v_fmac_f32_e32 v49, v52, v47
	v_fma_f32 v46, -v46, v49, v48
	v_div_fmas_f32 v46, v46, v47, v49
	v_div_fixup_f32 v40, v46, v40, 2.0
	v_sub_f32_e32 v40, 1.0, v40
	v_add_f32_e32 v40, 1.0, v40
	v_mul_f32_e32 v40, v41, v40
	v_bfe_u32 v41, v40, 16, 1
	v_add3_u32 v46, v40, v41, s31
	v_lshl_add_u64 v[40:41], s[28:29], 0, v[44:45]
	global_store_short_d16_hi v[40:41], v46, off
	v_or_b32_e32 v40, 34, v82
	v_mov_b32_e32 v41, v83
	v_lshlrev_b64 v[40:41], 9, v[40:41]
	v_lshl_add_u64 v[40:41], v[40:41], 0, v[50:51]
	v_lshlrev_b64 v[40:41], 1, v[40:41]
	v_lshl_add_u64 v[44:45], s[8:9], 0, v[40:41]
	v_lshl_add_u64 v[40:41], s[28:29], 0, v[40:41]
	s_waitcnt vmcnt(3)
; __device__ __forceinline__ float bf2f(bf16_t v) { return __uint_as_float(((unsigned)v) << 16); }
; __device__ __forceinline__ bf16_t f2bf(float f) { unsigned u = __float_as_uint(f); u += 0x7FFFu + ((u >> 16) & 1u); return (bf16_t)(u >> 16); }
; __device__ __forceinline__ void s5_bu16(const S5Frag& f, const bf16x8 uf, float* buL, int lane) {
;     const int jj = lane & 15, quad = lane >> 4;
; #pragma unroll
;     for (int nt = 0; nt < 4; ++nt) {
;         const f32x4 z = (f32x4){0.f, 0.f, 0.f, 0.f};
;         const f32x4 dre = __builtin_amdgcn_mfma_f32_16x16x32_bf16(uf, f.bfr[nt], z, 0, 0, 0);
;         const f32x4 dim = __builtin_amdgcn_mfma_f32_16x16x32_bf16(uf, f.bfr[nt + 4], z, 0, 0, 0);
; #pragma unroll
;         for (int r = 0; r < 4; ++r) *(f32x2*)(buL + ((4 * quad + r) * 64 + 16 * nt + jj) * 2) = (f32x2){dre[r], dim[r]};
;     }
; }
; __device__ __forceinline__ void s5_pass2_item(PP p, unsigned char* shm, int item, int l) {
;     ...
;         const f32x4 y = y0 + y1;
; #pragma unroll
;         for (int r = 0; r < 4; ++r) { const int tl = sc * 16 + quad * 4 + r;
;             const float v = y[r] + dsk * bf2f(proj[PJ_UA + (row0 + tl) * 512 + g * 16 + cc]);
;             const float z = 0.7978845608028654f * (v + 0.044715f * v * v * v);
;             const float th = 1.0f - 2.0f / (__expf(2.0f * z) + 1.0f);
;             Gout[(row0 + tl) * 512 + g * 16 + cc] = f2bf(0.5f * v * (1.0f + th)); }
	v_lshlrev_b32_e32 v44, 16, v210
	v_fma_f32 v42, v54, v44, v42
	v_mul_f32_e32 v44, 0x3d372713, v42
	v_mul_f32_e32 v44, v42, v44
	v_fma_f32 v44, v42, v44, v42
	v_mul_f32_e32 v44, 0x3f4c422a, v44
	v_add_f32_e32 v44, v44, v44
	v_mul_f32_e32 v44, 0x3fb8aa3b, v44
	v_exp_f32_e32 v44, v44
	v_mul_f32_e32 v42, 0.5, v42
	v_add_f32_e32 v44, 1.0, v44
	v_div_scale_f32 v45, s[2:3], v44, v44, 2.0
	v_rcp_f32_e32 v46, v45
	s_nop 0
	v_fma_f32 v47, -v45, v46, 1.0
	v_fmac_f32_e32 v46, v47, v46
	v_div_scale_f32 v47, vcc, 2.0, v44, 2.0
	v_mul_f32_e32 v48, v47, v46
	v_fma_f32 v49, -v45, v48, v47
	v_fmac_f32_e32 v48, v49, v46
	v_fma_f32 v45, -v45, v48, v47
	v_div_fmas_f32 v45, v45, v46, v48
	v_div_fixup_f32 v44, v45, v44, 2.0
	v_sub_f32_e32 v44, 1.0, v44
	v_add_f32_e32 v44, 1.0, v44
	v_mul_f32_e32 v42, v42, v44
	v_bfe_u32 v44, v42, 16, 1
	v_add3_u32 v42, v42, v44, s31
	global_store_short_d16_hi v[40:41], v42, off
	v_or_b32_e32 v40, 35, v82
	v_mov_b32_e32 v41, v83
	v_lshlrev_b64 v[40:41], 9, v[40:41]
	v_lshl_add_u64 v[40:41], v[40:41], 0, v[50:51]
	v_lshlrev_b64 v[40:41], 1, v[40:41]
	v_lshl_add_u64 v[44:45], s[8:9], 0, v[40:41]
	v_lshl_add_u64 v[40:41], s[28:29], 0, v[40:41]
	s_waitcnt vmcnt(3)
	v_lshlrev_b32_e32 v42, 16, v211
	v_fmac_f32_e32 v43, v54, v42
	v_mul_f32_e32 v42, 0x3d372713, v43
	v_mul_f32_e32 v42, v43, v42
	v_fma_f32 v42, v43, v42, v43
	v_mul_f32_e32 v42, 0x3f4c422a, v42
	v_add_f32_e32 v42, v42, v42
	v_mul_f32_e32 v42, 0x3fb8aa3b, v42
	v_exp_f32_e32 v42, v42
	v_mul_f32_e32 v43, 0.5, v43
	v_add_f32_e32 v42, 1.0, v42
	v_div_scale_f32 v44, s[2:3], v42, v42, 2.0
	v_rcp_f32_e32 v45, v44
	s_nop 0
	v_fma_f32 v46, -v44, v45, 1.0
	v_fmac_f32_e32 v45, v46, v45
	v_div_scale_f32 v46, vcc, 2.0, v42, 2.0
	v_mul_f32_e32 v47, v46, v45
	v_fma_f32 v48, -v44, v47, v46
	v_fmac_f32_e32 v47, v48, v45
	v_fma_f32 v44, -v44, v47, v46
	v_div_fmas_f32 v44, v44, v45, v47
	v_div_fixup_f32 v42, v44, v42, 2.0
	v_sub_f32_e32 v42, 1.0, v42
	v_add_f32_e32 v42, 1.0, v42
	v_mul_f32_e32 v42, v43, v42
	v_bfe_u32 v43, v42, 16, 1
	v_add3_u32 v42, v42, v43, s31
	global_store_short_d16_hi v[40:41], v42, off
	v_mfma_f32_16x16x32_bf16 v[40:43], v[2:5], v[26:29], 0
	s_nop 0
	v_mfma_f32_16x16x32_bf16 v[26:29], v[2:5], v[34:37], 0
	v_mfma_f32_16x16x32_bf16 v[2:5], v[2:5], v[6:9], 0
	s_nop 4
	v_mov_b32_e32 v34, v40
	s_nop 0
	v_mov_b32_e32 v35, v26
	v_mov_b32_e32 v26, v41
	v_mov_b32_e32 v36, v42
	v_mov_b32_e32 v37, v28
	v_mov_b32_e32 v40, v22
	v_mov_b32_e32 v41, v30
	v_mov_b32_e32 v30, v23
	v_mov_b32_e32 v22, v24
	v_mov_b32_e32 v23, v32
	ds_write2_b64 v108, v[36:37], v[22:23] offset0:128 offset1:144
	v_mov_b32_e32 v23, v14
	v_mov_b32_e32 v14, v19
	v_mov_b32_e32 v6, v10
	v_mov_b32_e32 v7, v2
	v_mov_b32_e32 v2, v11
	v_mov_b32_e32 v28, v43
	v_mov_b32_e32 v32, v25
	v_mov_b32_e32 v22, v18
	ds_write2_b64 v108, v[30:31], v[14:15] offset0:80 offset1:96
	v_mov_b32_e32 v14, v20
	v_mov_b32_e32 v15, v16
	v_mov_b32_e32 v16, v21
	ds_write2st64_b64 v99, v[6:7], v[2:3] offset0:8 offset1:9
	v_mov_b32_e32 v2, v12
	v_mov_b32_e32 v3, v4
	v_mov_b32_e32 v4, v13
	ds_write2_b64 v108, v[34:35], v[40:41] offset1:16
	ds_write2_b64 v108, v[22:23], v[26:27] offset0:32 offset1:64
	ds_write2_b64 v108, v[14:15], v[28:29] offset0:160 offset1:192
	ds_write2_b64 v108, v[32:33], v[16:17] offset0:208 offset1:224
	ds_write2st64_b64 v99, v[2:3], v[4:5] offset0:10 offset1:11
	s_waitcnt lgkmcnt(0)
	s_nop 0
	ds_read_b64 v[140:141], v90 offset:4096
	ds_read_b64 v[142:143], v90 offset:4608
	ds_read_b64 v[144:145], v90 offset:5120
	ds_read_b64 v[146:147], v90 offset:5632
	ds_read_b64 v[148:149], v90 offset:6144
	ds_read_b64 v[150:151], v90 offset:6656
	ds_read_b64 v[152:153], v90 offset:7168
	ds_read_b64 v[154:155], v90 offset:7680
	v_xor_b32_e32 v4, 0x80000000, v39
	v_mov_b32_e32 v5, v38
	v_pk_mul_f32 v[4:5], v[0:1], v[4:5] op_sel_hi:[0,1]
	v_pk_fma_f32 v[4:5], v[84:85], v[38:39], v[4:5] op_sel_hi:[0,1,1]
	s_waitcnt lgkmcnt(7)
	v_pk_add_f32 v[2:3], v[4:5], v[140:141]
	ds_write2st64_b32 v98, v2, v3 offset1:1
	v_xor_b32_e32 v6, 0x80000000, v3
	v_mov_b32_e32 v7, v2
	v_pk_mul_f32 v[6:7], v[0:1], v[6:7] op_sel_hi:[0,1]
	v_pk_fma_f32 v[2:3], v[84:85], v[2:3], v[6:7] op_sel_hi:[0,1,1]
	s_waitcnt lgkmcnt(7)
	v_pk_add_f32 v[2:3], v[142:143], v[2:3]
	ds_write2_b32 v98, v2, v3 offset0:132 offset1:196
	v_xor_b32_e32 v6, 0x80000000, v3
	v_mov_b32_e32 v7, v2
	v_pk_mul_f32 v[6:7], v[0:1], v[6:7] op_sel_hi:[0,1]
	v_pk_fma_f32 v[2:3], v[84:85], v[2:3], v[6:7] op_sel_hi:[0,1,1]
	s_waitcnt lgkmcnt(7)
	v_pk_add_f32 v[2:3], v[144:145], v[2:3]
	ds_write2st64_b32 v78, v2, v3 offset0:4 offset1:5
	v_xor_b32_e32 v6, 0x80000000, v3
	v_mov_b32_e32 v7, v2
	v_pk_mul_f32 v[6:7], v[0:1], v[6:7] op_sel_hi:[0,1]
	v_pk_fma_f32 v[2:3], v[84:85], v[2:3], v[6:7] op_sel_hi:[0,1,1]
	s_waitcnt lgkmcnt(7)
	v_pk_add_f32 v[2:3], v[146:147], v[2:3]
	ds_write2st64_b32 v79, v2, v3 offset0:6 offset1:7
	v_xor_b32_e32 v6, 0x80000000, v3
	v_mov_b32_e32 v7, v2
	v_pk_mul_f32 v[6:7], v[0:1], v[6:7] op_sel_hi:[0,1]
	v_pk_fma_f32 v[2:3], v[84:85], v[2:3], v[6:7] op_sel_hi:[0,1,1]
	s_waitcnt lgkmcnt(7)
	v_pk_add_f32 v[2:3], v[148:149], v[2:3]
	ds_write2st64_b32 v80, v2, v3 offset0:8 offset1:9
	v_xor_b32_e32 v6, 0x80000000, v3
	v_mov_b32_e32 v7, v2
	v_pk_mul_f32 v[6:7], v[0:1], v[6:7] op_sel_hi:[0,1]
	v_pk_fma_f32 v[2:3], v[84:85], v[2:3], v[6:7] op_sel_hi:[0,1,1]
	s_waitcnt lgkmcnt(7)
	v_pk_add_f32 v[2:3], v[150:151], v[2:3]
	ds_write2st64_b32 v81, v2, v3 offset0:10 offset1:11
	v_xor_b32_e32 v6, 0x80000000, v3
	v_mov_b32_e32 v7, v2
	v_pk_mul_f32 v[6:7], v[0:1], v[6:7] op_sel_hi:[0,1]
	v_pk_fma_f32 v[2:3], v[84:85], v[2:3], v[6:7] op_sel_hi:[0,1,1]
	s_waitcnt lgkmcnt(7)
; __device__ __forceinline__ float bf2f(bf16_t v) { return __uint_as_float(((unsigned)v) << 16); }
; __device__ __forceinline__ void s5_pass2_item(PP p, unsigned char* shm, int item, int l) {
;     ...
; #pragma unroll
;         for (int t = 0; t < 16; ++t) { s5_rec(q, *(const f32x2*)(buL + (t * 64 + lane) * 2), x); xs[t * 132 + lane] = x.x; xs[t * 132 + 64 + lane] = x.y; }
;         __syncthreads();
;         f32x4 y0 = (f32x4){0.f, 0.f, 0.f, 0.f}, y1 = y0;
;         const f32x4* xrow = (const f32x4*)(xs + cc * 132 + quad * 32);
; #pragma unroll
;         for (int i = 0; i < 8; ++i) { const f32x4 xv = xrow[i];
;             y0 = __builtin_amdgcn_mfma_f32_16x16x4f32(xv[0], cmr[4 * i + 0], y0, 0, 0, 0);
;             y1 = __builtin_amdgcn_mfma_f32_16x16x4f32(xv[1], cmr[4 * i + 1], y1, 0, 0, 0);
;             y0 = __builtin_amdgcn_mfma_f32_16x16x4f32(xv[2], cmr[4 * i + 2], y0, 0, 0, 0);
;             y1 = __builtin_amdgcn_mfma_f32_16x16x4f32(xv[3], cmr[4 * i + 3], y1, 0, 0, 0); }
;         const f32x4 y = y0 + y1;
; #pragma unroll
;         for (int r = 0; r < 4; ++r) { const int tl = sc * 16 + quad * 4 + r;
;             const float v = y[r] + dsk * bf2f(proj[PJ_UA + (row0 + tl) * 512 + g * 16 + cc]);
	v_pk_add_f32 v[2:3], v[152:153], v[2:3]
	ds_write2st64_b32 v86, v2, v3 offset0:12 offset1:13
	v_xor_b32_e32 v6, 0x80000000, v3
	v_mov_b32_e32 v7, v2
	v_pk_mul_f32 v[6:7], v[0:1], v[6:7] op_sel_hi:[0,1]
	v_pk_fma_f32 v[2:3], v[84:85], v[2:3], v[6:7] op_sel_hi:[0,1,1]
	s_waitcnt lgkmcnt(7)
	v_pk_add_f32 v[2:3], v[154:155], v[2:3]
	ds_write2st64_b32 v87, v2, v3 offset0:14 offset1:15
	ds_read_b64 v[140:141], v90 offset:8192
	ds_read_b64 v[142:143], v90 offset:8704
	ds_read_b64 v[144:145], v90 offset:9216
	ds_read_b64 v[146:147], v90 offset:9728
	ds_read_b64 v[148:149], v90 offset:10240
	ds_read_b64 v[150:151], v90 offset:10752
	ds_read_b64 v[152:153], v90 offset:11264
	ds_read_b64 v[154:155], v90 offset:11776
	v_xor_b32_e32 v6, 0x80000000, v3
	v_mov_b32_e32 v7, v2
	v_pk_mul_f32 v[6:7], v[0:1], v[6:7] op_sel_hi:[0,1]
	v_pk_fma_f32 v[2:3], v[84:85], v[2:3], v[6:7] op_sel_hi:[0,1,1]
	s_waitcnt lgkmcnt(7)
	v_pk_add_f32 v[2:3], v[140:141], v[2:3]
	ds_write2st64_b32 v100, v2, v3 offset0:16 offset1:17
	v_xor_b32_e32 v6, 0x80000000, v3
	v_mov_b32_e32 v7, v2
	v_pk_mul_f32 v[6:7], v[0:1], v[6:7] op_sel_hi:[0,1]
	v_pk_fma_f32 v[2:3], v[84:85], v[2:3], v[6:7] op_sel_hi:[0,1,1]
	s_waitcnt lgkmcnt(7)
	v_pk_add_f32 v[2:3], v[142:143], v[2:3]
	ds_write2st64_b32 v101, v2, v3 offset0:18 offset1:19
	v_xor_b32_e32 v6, 0x80000000, v3
	v_mov_b32_e32 v7, v2
	v_pk_mul_f32 v[6:7], v[0:1], v[6:7] op_sel_hi:[0,1]
	v_pk_fma_f32 v[2:3], v[84:85], v[2:3], v[6:7] op_sel_hi:[0,1,1]
	s_waitcnt lgkmcnt(7)
	v_pk_add_f32 v[2:3], v[144:145], v[2:3]
	ds_write2st64_b32 v102, v2, v3 offset0:20 offset1:21
	v_xor_b32_e32 v6, 0x80000000, v3
	v_mov_b32_e32 v7, v2
	v_pk_mul_f32 v[6:7], v[0:1], v[6:7] op_sel_hi:[0,1]
	v_pk_fma_f32 v[2:3], v[84:85], v[2:3], v[6:7] op_sel_hi:[0,1,1]
	s_waitcnt lgkmcnt(7)
	v_pk_add_f32 v[2:3], v[146:147], v[2:3]
	ds_write2st64_b32 v103, v2, v3 offset0:22 offset1:23
	v_xor_b32_e32 v6, 0x80000000, v3
	v_mov_b32_e32 v7, v2
	v_pk_mul_f32 v[6:7], v[0:1], v[6:7] op_sel_hi:[0,1]
	v_pk_fma_f32 v[2:3], v[84:85], v[2:3], v[6:7] op_sel_hi:[0,1,1]
	s_waitcnt lgkmcnt(7)
	v_pk_add_f32 v[2:3], v[148:149], v[2:3]
	ds_write2st64_b32 v104, v2, v3 offset0:24 offset1:25
	v_xor_b32_e32 v6, 0x80000000, v3
	v_mov_b32_e32 v7, v2
	v_pk_mul_f32 v[6:7], v[0:1], v[6:7] op_sel_hi:[0,1]
	v_pk_fma_f32 v[2:3], v[84:85], v[2:3], v[6:7] op_sel_hi:[0,1,1]
	s_waitcnt lgkmcnt(7)
	v_pk_add_f32 v[2:3], v[150:151], v[2:3]
	ds_write2st64_b32 v105, v2, v3 offset0:26 offset1:27
	v_xor_b32_e32 v6, 0x80000000, v3
	v_mov_b32_e32 v7, v2
	v_pk_mul_f32 v[6:7], v[0:1], v[6:7] op_sel_hi:[0,1]
	v_pk_fma_f32 v[2:3], v[84:85], v[2:3], v[6:7] op_sel_hi:[0,1,1]
	s_waitcnt lgkmcnt(7)
	v_pk_add_f32 v[2:3], v[152:153], v[2:3]
	ds_write2st64_b32 v106, v2, v3 offset0:28 offset1:29
	v_xor_b32_e32 v6, 0x80000000, v3
	v_mov_b32_e32 v7, v2
	v_pk_mul_f32 v[6:7], v[0:1], v[6:7] op_sel_hi:[0,1]
	v_pk_fma_f32 v[2:3], v[84:85], v[2:3], v[6:7] op_sel_hi:[0,1,1]
	s_waitcnt lgkmcnt(7)
	v_pk_add_f32 v[2:3], v[154:155], v[2:3]
	ds_write2st64_b32 v107, v2, v3 offset0:30 offset1:31
	s_waitcnt lgkmcnt(0)
	s_nop 0
	v_or_b32_e32 v216, 48, v82
	v_mov_b32_e32 v217, v83
	v_lshlrev_b64 v[216:217], 9, v[216:217]
	v_lshl_add_u64 v[216:217], v[216:217], 0, v[50:51]
	v_lshlrev_b64 v[216:217], 1, v[216:217]
	v_lshl_add_u64 v[216:217], s[8:9], 0, v[216:217]
	global_load_ushort v212, v[216:217], off
	global_load_ushort v213, v[216:217], off offset:1024
	global_load_ushort v214, v[216:217], off offset:2048
	global_load_ushort v215, v[216:217], off offset:3072
	ds_read_b128 v[2:5], v89
	ds_read_b128 v[6:9], v89 offset:16
	ds_read_b128 v[10:13], v89 offset:32
	ds_read_b128 v[14:17], v89 offset:48
	s_waitcnt lgkmcnt(3)
	v_mfma_f32_16x16x4_f32 v[18:21], v2, v97, 0
	v_mfma_f32_16x16x4_f32 v[22:25], v3, v96, 0
	v_mfma_f32_16x16x4_f32 v[18:21], v4, v95, v[18:21]
	v_mfma_f32_16x16x4_f32 v[2:5], v5, v94, v[22:25]
	s_waitcnt lgkmcnt(2)
	v_mfma_f32_16x16x4_f32 v[18:21], v6, v93, v[18:21]
	v_mfma_f32_16x16x4_f32 v[2:5], v7, v92, v[2:5]
	v_mfma_f32_16x16x4_f32 v[18:21], v8, v91, v[18:21]
	v_mfma_f32_16x16x4_f32 v[2:5], v9, v88, v[2:5]
	s_waitcnt lgkmcnt(1)
	v_mfma_f32_16x16x4_f32 v[6:9], v10, v85, v[18:21]
	v_mfma_f32_16x16x4_f32 v[2:5], v11, v55, v[2:5]
	v_mfma_f32_16x16x4_f32 v[6:9], v12, v56, v[6:9]
	v_mfma_f32_16x16x4_f32 v[2:5], v13, v57, v[2:5]
	ds_read_b128 v[10:13], v89 offset:64
	s_waitcnt lgkmcnt(1)
	v_mfma_f32_16x16x4_f32 v[6:9], v14, v58, v[6:9]
	v_mfma_f32_16x16x4_f32 v[2:5], v15, v59, v[2:5]
	v_mfma_f32_16x16x4_f32 v[6:9], v16, v60, v[6:9]
	v_mfma_f32_16x16x4_f32 v[2:5], v17, v61, v[2:5]
	s_waitcnt lgkmcnt(0)
	v_mfma_f32_16x16x4_f32 v[6:9], v10, v62, v[6:9]
	v_mfma_f32_16x16x4_f32 v[2:5], v11, v63, v[2:5]
	v_mfma_f32_16x16x4_f32 v[6:9], v12, v64, v[6:9]
	v_mfma_f32_16x16x4_f32 v[2:5], v13, v65, v[2:5]
	ds_read_b128 v[10:13], v89 offset:80
	s_waitcnt lgkmcnt(0)
	v_mfma_f32_16x16x4_f32 v[6:9], v10, v66, v[6:9]
	v_mfma_f32_16x16x4_f32 v[2:5], v11, v67, v[2:5]
	v_mfma_f32_16x16x4_f32 v[6:9], v12, v68, v[6:9]
	v_mfma_f32_16x16x4_f32 v[2:5], v13, v69, v[2:5]
	ds_read_b128 v[10:13], v89 offset:96
	s_waitcnt lgkmcnt(0)
; __device__ __forceinline__ float bf2f(bf16_t v) { return __uint_as_float(((unsigned)v) << 16); }
; __device__ __forceinline__ bf16_t f2bf(float f) { unsigned u = __float_as_uint(f); u += 0x7FFFu + ((u >> 16) & 1u); return (bf16_t)(u >> 16); }
; __device__ __forceinline__ void s5_pass2_item(PP p, unsigned char* shm, int item, int l) {
;     ...
;         f32x4 y0 = (f32x4){0.f, 0.f, 0.f, 0.f}, y1 = y0;
;         const f32x4* xrow = (const f32x4*)(xs + cc * 132 + quad * 32);
; #pragma unroll
;         for (int i = 0; i < 8; ++i) { const f32x4 xv = xrow[i];
;             y0 = __builtin_amdgcn_mfma_f32_16x16x4f32(xv[0], cmr[4 * i + 0], y0, 0, 0, 0);
;             y1 = __builtin_amdgcn_mfma_f32_16x16x4f32(xv[1], cmr[4 * i + 1], y1, 0, 0, 0);
;             y0 = __builtin_amdgcn_mfma_f32_16x16x4f32(xv[2], cmr[4 * i + 2], y0, 0, 0, 0);
;             y1 = __builtin_amdgcn_mfma_f32_16x16x4f32(xv[3], cmr[4 * i + 3], y1, 0, 0, 0); }
;         const f32x4 y = y0 + y1;
; #pragma unroll
;         for (int r = 0; r < 4; ++r) { const int tl = sc * 16 + quad * 4 + r;
;             const float v = y[r] + dsk * bf2f(proj[PJ_UA + (row0 + tl) * 512 + g * 16 + cc]);
;             const float z = 0.7978845608028654f * (v + 0.044715f * v * v * v);
;             const float th = 1.0f - 2.0f / (__expf(2.0f * z) + 1.0f);
;             Gout[(row0 + tl) * 512 + g * 16 + cc] = f2bf(0.5f * v * (1.0f + th)); }
;         __syncthreads();
;     }
	v_mfma_f32_16x16x4_f32 v[6:9], v10, v70, v[6:9]
	v_mfma_f32_16x16x4_f32 v[2:5], v11, v71, v[2:5]
	v_mfma_f32_16x16x4_f32 v[6:9], v12, v72, v[6:9]
	v_mfma_f32_16x16x4_f32 v[2:5], v13, v73, v[2:5]
	ds_read_b128 v[10:13], v89 offset:112
	s_waitcnt lgkmcnt(0)
	v_mfma_f32_16x16x4_f32 v[6:9], v10, v74, v[6:9]
	v_mfma_f32_16x16x4_f32 v[2:5], v11, v75, v[2:5]
	v_mfma_f32_16x16x4_f32 v[6:9], v12, v76, v[6:9]
	v_mfma_f32_16x16x4_f32 v[10:13], v13, v77, v[2:5]
	s_nop 9
	v_pk_add_f32 v[4:5], v[6:7], v[10:11]
	v_or_b32_e32 v6, 48, v82
	v_mov_b32_e32 v7, v83
	v_lshlrev_b64 v[6:7], 9, v[6:7]
	v_lshl_add_u64 v[6:7], v[6:7], 0, v[50:51]
	v_lshlrev_b64 v[6:7], 1, v[6:7]
	v_pk_add_f32 v[2:3], v[8:9], v[12:13]
	v_lshl_add_u64 v[8:9], s[8:9], 0, v[6:7]
	v_lshl_add_u64 v[6:7], s[28:29], 0, v[6:7]
	s_waitcnt vmcnt(3)
	v_lshlrev_b32_e32 v0, 16, v212
	v_fma_f32 v0, v54, v0, v4
	v_mul_f32_e32 v4, 0x3d372713, v0
	v_mul_f32_e32 v4, v0, v4
	v_fma_f32 v4, v0, v4, v0
	v_mul_f32_e32 v4, 0x3f4c422a, v4
	v_add_f32_e32 v4, v4, v4
	v_mul_f32_e32 v4, 0x3fb8aa3b, v4
	v_exp_f32_e32 v4, v4
	v_mul_f32_e32 v0, 0.5, v0
	v_add_f32_e32 v4, 1.0, v4
	v_div_scale_f32 v8, s[2:3], v4, v4, 2.0
	v_rcp_f32_e32 v9, v8
	s_nop 0
	v_fma_f32 v10, -v8, v9, 1.0
	v_fmac_f32_e32 v9, v10, v9
	v_div_scale_f32 v10, vcc, 2.0, v4, 2.0
	v_mul_f32_e32 v11, v10, v9
	v_fma_f32 v12, -v8, v11, v10
	v_fmac_f32_e32 v11, v12, v9
	v_fma_f32 v8, -v8, v11, v10
	v_div_fmas_f32 v8, v8, v9, v11
	v_div_fixup_f32 v4, v8, v4, 2.0
	v_sub_f32_e32 v4, 1.0, v4
	v_add_f32_e32 v4, 1.0, v4
	v_mul_f32_e32 v0, v0, v4
	v_bfe_u32 v4, v0, 16, 1
	v_add3_u32 v0, v0, v4, s31
	global_store_short_d16_hi v[6:7], v0, off
	v_or_b32_e32 v6, 49, v82
	v_mov_b32_e32 v7, v83
	v_lshlrev_b64 v[6:7], 9, v[6:7]
	v_lshl_add_u64 v[6:7], v[6:7], 0, v[50:51]
	v_lshlrev_b64 v[6:7], 1, v[6:7]
	v_lshl_add_u64 v[8:9], s[8:9], 0, v[6:7]
	s_waitcnt vmcnt(3)
	v_lshlrev_b32_e32 v0, 16, v213
	v_fmac_f32_e32 v5, v54, v0
	v_mul_f32_e32 v0, 0x3d372713, v5
	v_mul_f32_e32 v0, v5, v0
	v_fma_f32 v0, v5, v0, v5
	v_mul_f32_e32 v0, 0x3f4c422a, v0
	v_add_f32_e32 v0, v0, v0
	v_mul_f32_e32 v0, 0x3fb8aa3b, v0
	v_exp_f32_e32 v0, v0
	s_nop 0
	v_add_f32_e32 v0, 1.0, v0
	v_div_scale_f32 v4, s[2:3], v0, v0, 2.0
	v_rcp_f32_e32 v8, v4
	s_nop 0
	v_fma_f32 v9, -v4, v8, 1.0
	v_fmac_f32_e32 v8, v9, v8
	v_div_scale_f32 v9, vcc, 2.0, v0, 2.0
	v_mul_f32_e32 v10, v9, v8
	v_fma_f32 v11, -v4, v10, v9
	v_fmac_f32_e32 v10, v11, v8
	v_fma_f32 v4, -v4, v10, v9
	v_div_fmas_f32 v4, v4, v8, v10
	v_div_fixup_f32 v0, v4, v0, 2.0
	v_sub_f32_e32 v0, 1.0, v0
	v_mul_f32_e32 v4, 0.5, v5
	v_add_f32_e32 v0, 1.0, v0
	v_mul_f32_e32 v0, v4, v0
	v_bfe_u32 v4, v0, 16, 1
	v_add3_u32 v0, v0, v4, s31
	v_lshl_add_u64 v[4:5], s[28:29], 0, v[6:7]
	global_store_short_d16_hi v[4:5], v0, off
	v_or_b32_e32 v4, 50, v82
	v_mov_b32_e32 v5, v83
	v_lshlrev_b64 v[4:5], 9, v[4:5]
	v_lshl_add_u64 v[4:5], v[4:5], 0, v[50:51]
	v_lshlrev_b64 v[4:5], 1, v[4:5]
	v_lshl_add_u64 v[6:7], s[8:9], 0, v[4:5]
	v_lshl_add_u64 v[4:5], s[28:29], 0, v[4:5]
	v_or_b32_e32 v82, 51, v82
	s_waitcnt vmcnt(3)
	v_lshlrev_b32_e32 v0, 16, v214
	v_fma_f32 v0, v54, v0, v2
	v_mul_f32_e32 v2, 0x3d372713, v0
	v_mul_f32_e32 v2, v0, v2
	v_fma_f32 v2, v0, v2, v0
	v_mul_f32_e32 v2, 0x3f4c422a, v2
	v_add_f32_e32 v2, v2, v2
	v_mul_f32_e32 v2, 0x3fb8aa3b, v2
	v_exp_f32_e32 v2, v2
	v_mul_f32_e32 v0, 0.5, v0
	v_add_f32_e32 v2, 1.0, v2
	v_div_scale_f32 v6, s[2:3], v2, v2, 2.0
	v_rcp_f32_e32 v7, v6
	s_nop 0
	v_fma_f32 v8, -v6, v7, 1.0
	v_fmac_f32_e32 v7, v8, v7
	v_div_scale_f32 v8, vcc, 2.0, v2, 2.0
	v_mul_f32_e32 v9, v8, v7
	v_fma_f32 v10, -v6, v9, v8
	v_fmac_f32_e32 v9, v10, v7
	v_fma_f32 v6, -v6, v9, v8
	v_div_fmas_f32 v6, v6, v7, v9
	v_div_fixup_f32 v2, v6, v2, 2.0
	v_sub_f32_e32 v2, 1.0, v2
	v_add_f32_e32 v2, 1.0, v2
	v_mul_f32_e32 v0, v0, v2
	v_bfe_u32 v2, v0, 16, 1
	v_add3_u32 v0, v0, v2, s31
	global_store_short_d16_hi v[4:5], v0, off
	v_lshlrev_b64 v[4:5], 9, v[82:83]
	v_lshl_add_u64 v[4:5], v[4:5], 0, v[50:51]
	v_lshlrev_b64 v[4:5], 1, v[4:5]
	v_lshl_add_u64 v[6:7], s[8:9], 0, v[4:5]
	s_waitcnt vmcnt(3)
	v_lshlrev_b32_e32 v0, 16, v215
	v_fmac_f32_e32 v3, v54, v0
	v_mul_f32_e32 v0, 0x3d372713, v3
	v_mul_f32_e32 v0, v3, v0
	v_fma_f32 v0, v3, v0, v3
	v_mul_f32_e32 v0, 0x3f4c422a, v0
	v_add_f32_e32 v0, v0, v0
	v_mul_f32_e32 v0, 0x3fb8aa3b, v0
	v_exp_f32_e32 v0, v0
	s_nop 0
	v_add_f32_e32 v0, 1.0, v0
	v_div_scale_f32 v2, s[2:3], v0, v0, 2.0
	v_rcp_f32_e32 v6, v2
	s_nop 0
	v_fma_f32 v7, -v2, v6, 1.0
	v_fmac_f32_e32 v6, v7, v6
	v_div_scale_f32 v7, vcc, 2.0, v0, 2.0
	v_mul_f32_e32 v8, v7, v6
	v_fma_f32 v9, -v2, v8, v7
	v_fmac_f32_e32 v8, v9, v6
	v_fma_f32 v2, -v2, v8, v7
	v_div_fmas_f32 v2, v2, v6, v8
	v_div_fixup_f32 v0, v2, v0, 2.0
	v_sub_f32_e32 v0, 1.0, v0
	v_mul_f32_e32 v2, 0.5, v3
	v_add_f32_e32 v0, 1.0, v0
	v_mul_f32_e32 v0, v2, v0
	v_bfe_u32 v2, v0, 16, 1
	v_add3_u32 v0, v0, v2, s31
	v_lshl_add_u64 v[2:3], s[28:29], 0, v[4:5]
	global_store_short_d16_hi v[2:3], v0, off
	s_barrier
	s_cbranch_scc1 .LBB0_718
